# prompt conv: LayerNorm-stats barrier waits on the LDS counter only, so the next block's / pool-mix unit's LDS-DMA staging overlaps statistics+normalise+store
# baseline (speedup 1.0000x reference)
; #define LAS __attribute__((address_space(3)))
; __device__ __forceinline__ float bf_lo(unsigned w) { return __uint_as_float(w << 16); }
; __device__ __forceinline__ float bf_hi(unsigned w) { return __uint_as_float(w & 0xffff0000u); }
; __device__ __forceinline__ void p2_conv_unit_prompt(Frame& F, int unit, int next_pm, const ConvW& cw, size_t src_off = WS_A, size_t dst_off = WS_CACT) {
;     ...
; #pragma unroll
;         for (int rg = 0; rg < CV_ROWS; rg += 8) {
;             unsigned w2[8], w1[8];
; #pragma unroll
;             for (int i = 0; i < 8; ++i) if (rg + i < CV_ROWS) { const LAS unsigned char* rp = S + (rg + i) * (DCONV * 2) + ((rg + i) < CW - 1 ? ringLo : ringHi);
;                 w2[i] = *(const LAS unsigned*)(rp + p * 2u); w1[i] = *(const LAS unsigned short*)(rp + q * 2u); }
; #pragma unroll
;             for (int i = 0; i < 8; ++i) if (rg + i < CV_ROWS) { const int rr = rg + i; const f32x2 vp = (f32x2){bf_lo(w2[i]), bf_hi(w2[i])}; const float vq = bf_lo(w1[i]);
; #pragma unroll
;                 for (int t = 0; t < 16; ++t) { const int j = rr - t; if (j >= 0 && j < CW) { ap[t] += wp[j] * vp; aq[t] += wq[j] * vq; } } }
;             __builtin_amdgcn_sched_barrier(0); }
.LBB0_480:
	v_lshlrev_b32_e32 v1, 16, v145
	v_lshlrev_b32_e32 v38, 16, v36
	v_and_b32_e32 v39, 0xffff0000, v36
	v_pk_fma_f32 v[38:39], v[114:115], v[38:39], v[120:121]
	v_fma_f32 v145, v190, v1, v197
	v_lshlrev_b32_e32 v36, 16, v37
	v_and_b32_e32 v37, 0xffff0000, v37
	v_lshlrev_b32_e32 v1, 16, v144
	v_pk_fma_f32 v[38:39], v[116:117], v[36:37], v[38:39]
	v_fmac_f32_e32 v145, v191, v1
	v_pk_fma_f32 v[36:37], v[114:115], v[36:37], v[120:121]
	v_fma_f32 v144, v190, v1, v197
	v_lshlrev_b32_e32 v230, 16, v34
	v_and_b32_e32 v231, 0xffff0000, v34
	v_lshlrev_b32_e32 v1, 16, v143
	v_pk_fma_f32 v[38:39], v[118:119], v[230:231], v[38:39]
	v_fmac_f32_e32 v145, v192, v1
	v_pk_fma_f32 v[36:37], v[116:117], v[230:231], v[36:37]
	v_fmac_f32_e32 v144, v191, v1
	v_pk_fma_f32 v[230:231], v[114:115], v[230:231], v[120:121]
	v_fma_f32 v143, v190, v1, v197
	v_lshlrev_b32_e32 v34, 16, v35
	v_and_b32_e32 v35, 0xffff0000, v35
	v_lshlrev_b32_e32 v1, 16, v142
	v_pk_fma_f32 v[38:39], v[58:59], v[34:35], v[38:39]
	v_fmac_f32_e32 v145, v193, v1
	v_pk_fma_f32 v[36:37], v[118:119], v[34:35], v[36:37]
	v_fmac_f32_e32 v144, v192, v1
	v_pk_fma_f32 v[230:231], v[116:117], v[34:35], v[230:231]
	v_fmac_f32_e32 v143, v191, v1
	v_pk_fma_f32 v[34:35], v[114:115], v[34:35], v[120:121]
	v_fma_f32 v142, v190, v1, v197
	v_lshlrev_b32_e32 v232, 16, v32
	v_and_b32_e32 v233, 0xffff0000, v32
	v_lshlrev_b32_e32 v1, 16, v141
	v_pk_fma_f32 v[38:39], v[60:61], v[232:233], v[38:39]
	v_fmac_f32_e32 v145, v194, v1
	v_pk_fma_f32 v[36:37], v[58:59], v[232:233], v[36:37]
	v_fmac_f32_e32 v144, v193, v1
	v_pk_fma_f32 v[230:231], v[118:119], v[232:233], v[230:231]
	v_fmac_f32_e32 v143, v192, v1
	v_pk_fma_f32 v[34:35], v[116:117], v[232:233], v[34:35]
	v_fmac_f32_e32 v142, v191, v1
	v_pk_fma_f32 v[232:233], v[114:115], v[232:233], v[120:121]
	v_fma_f32 v141, v190, v1, v197
	v_lshlrev_b32_e32 v32, 16, v33
	v_and_b32_e32 v33, 0xffff0000, v33
	v_lshlrev_b32_e32 v1, 16, v140
	v_pk_fma_f32 v[38:39], v[62:63], v[32:33], v[38:39]
	v_fmac_f32_e32 v145, v195, v1
	v_pk_fma_f32 v[36:37], v[60:61], v[32:33], v[36:37]
	v_fmac_f32_e32 v144, v194, v1
	v_pk_fma_f32 v[230:231], v[58:59], v[32:33], v[230:231]
	v_fmac_f32_e32 v143, v193, v1
	v_pk_fma_f32 v[34:35], v[118:119], v[32:33], v[34:35]
	v_fmac_f32_e32 v142, v192, v1
	v_pk_fma_f32 v[232:233], v[116:117], v[32:33], v[232:233]
	v_fmac_f32_e32 v141, v191, v1
	v_pk_fma_f32 v[32:33], v[114:115], v[32:33], v[120:121]
	v_fma_f32 v140, v190, v1, v197
	v_lshlrev_b32_e32 v234, 16, v30
	v_and_b32_e32 v235, 0xffff0000, v30
	v_lshlrev_b32_e32 v1, 16, v139
	v_pk_fma_f32 v[38:39], v[64:65], v[234:235], v[38:39]
	v_fmac_f32_e32 v145, v196, v1
	v_pk_fma_f32 v[36:37], v[62:63], v[234:235], v[36:37]
	v_fmac_f32_e32 v144, v195, v1
	v_pk_fma_f32 v[230:231], v[60:61], v[234:235], v[230:231]
	v_fmac_f32_e32 v143, v194, v1
	v_pk_fma_f32 v[34:35], v[58:59], v[234:235], v[34:35]
	v_fmac_f32_e32 v142, v193, v1
	v_pk_fma_f32 v[232:233], v[118:119], v[234:235], v[232:233]
	v_fmac_f32_e32 v141, v192, v1
	v_pk_fma_f32 v[32:33], v[116:117], v[234:235], v[32:33]
	v_fmac_f32_e32 v140, v191, v1
	v_pk_fma_f32 v[234:235], v[114:115], v[234:235], v[120:121]
	v_fma_f32 v139, v190, v1, v197
	v_lshlrev_b32_e32 v30, 16, v31
	v_and_b32_e32 v31, 0xffff0000, v31
	v_lshlrev_b32_e32 v1, 16, v138
	v_pk_fma_f32 v[38:39], v[66:67], v[30:31], v[38:39]
	v_fmac_f32_e32 v145, v166, v1
	v_pk_fma_f32 v[36:37], v[64:65], v[30:31], v[36:37]
	v_fmac_f32_e32 v144, v196, v1
	v_pk_fma_f32 v[230:231], v[62:63], v[30:31], v[230:231]
	v_fmac_f32_e32 v143, v195, v1
	v_pk_fma_f32 v[34:35], v[60:61], v[30:31], v[34:35]
	v_fmac_f32_e32 v142, v194, v1
	v_pk_fma_f32 v[232:233], v[58:59], v[30:31], v[232:233]
	v_fmac_f32_e32 v141, v193, v1
	v_pk_fma_f32 v[32:33], v[118:119], v[30:31], v[32:33]
	v_fmac_f32_e32 v140, v192, v1
	v_pk_fma_f32 v[234:235], v[116:117], v[30:31], v[234:235]
	v_fmac_f32_e32 v139, v191, v1
	v_pk_fma_f32 v[30:31], v[114:115], v[30:31], v[120:121]
	v_fma_f32 v138, v190, v1, v197
	v_lshlrev_b32_e32 v236, 16, v28
	v_and_b32_e32 v237, 0xffff0000, v28
	v_lshlrev_b32_e32 v1, 16, v137
	v_pk_fma_f32 v[38:39], v[68:69], v[236:237], v[38:39]
	v_fmac_f32_e32 v145, v167, v1
	v_pk_fma_f32 v[36:37], v[66:67], v[236:237], v[36:37]
	v_fmac_f32_e32 v144, v166, v1
	v_pk_fma_f32 v[230:231], v[64:65], v[236:237], v[230:231]
	v_fmac_f32_e32 v143, v196, v1
	v_pk_fma_f32 v[34:35], v[62:63], v[236:237], v[34:35]
	v_fmac_f32_e32 v142, v195, v1
	v_pk_fma_f32 v[232:233], v[60:61], v[236:237], v[232:233]
	v_fmac_f32_e32 v141, v194, v1
	v_pk_fma_f32 v[32:33], v[58:59], v[236:237], v[32:33]
	v_fmac_f32_e32 v140, v193, v1
	v_pk_fma_f32 v[234:235], v[118:119], v[236:237], v[234:235]
	v_fmac_f32_e32 v139, v192, v1
	v_pk_fma_f32 v[30:31], v[116:117], v[236:237], v[30:31]
	v_fmac_f32_e32 v138, v191, v1
	v_pk_fma_f32 v[236:237], v[114:115], v[236:237], v[120:121]
	v_fma_f32 v137, v190, v1, v197
	v_lshlrev_b32_e32 v28, 16, v29
	v_and_b32_e32 v29, 0xffff0000, v29
	v_lshlrev_b32_e32 v1, 16, v136
	v_pk_fma_f32 v[38:39], v[70:71], v[28:29], v[38:39]
	v_fmac_f32_e32 v145, v168, v1
	v_pk_fma_f32 v[36:37], v[68:69], v[28:29], v[36:37]
	v_fmac_f32_e32 v144, v167, v1
	v_pk_fma_f32 v[230:231], v[66:67], v[28:29], v[230:231]
	v_fmac_f32_e32 v143, v166, v1
	v_pk_fma_f32 v[34:35], v[64:65], v[28:29], v[34:35]
	v_fmac_f32_e32 v142, v196, v1
	v_pk_fma_f32 v[232:233], v[62:63], v[28:29], v[232:233]
	v_fmac_f32_e32 v141, v195, v1
	v_pk_fma_f32 v[32:33], v[60:61], v[28:29], v[32:33]
	v_fmac_f32_e32 v140, v194, v1
	v_pk_fma_f32 v[234:235], v[58:59], v[28:29], v[234:235]
	v_fmac_f32_e32 v139, v193, v1
	v_pk_fma_f32 v[30:31], v[118:119], v[28:29], v[30:31]
; #define LAS __attribute__((address_space(3)))
; __device__ __forceinline__ float bf_lo(unsigned w) { return __uint_as_float(w << 16); }
; __device__ __forceinline__ float bf_hi(unsigned w) { return __uint_as_float(w & 0xffff0000u); }
; __device__ __forceinline__ void p2_conv_unit_prompt(Frame& F, int unit, int next_pm, const ConvW& cw, size_t src_off = WS_A, size_t dst_off = WS_CACT) {
;     ...
; #pragma unroll
;         for (int rg = 0; rg < CV_ROWS; rg += 8) {
;             unsigned w2[8], w1[8];
; #pragma unroll
;             for (int i = 0; i < 8; ++i) if (rg + i < CV_ROWS) { const LAS unsigned char* rp = S + (rg + i) * (DCONV * 2) + ((rg + i) < CW - 1 ? ringLo : ringHi);
;                 w2[i] = *(const LAS unsigned*)(rp + p * 2u); w1[i] = *(const LAS unsigned short*)(rp + q * 2u); }
; #pragma unroll
;             for (int i = 0; i < 8; ++i) if (rg + i < CV_ROWS) { const int rr = rg + i; const f32x2 vp = (f32x2){bf_lo(w2[i]), bf_hi(w2[i])}; const float vq = bf_lo(w1[i]);
; #pragma unroll
;                 for (int t = 0; t < 16; ++t) { const int j = rr - t; if (j >= 0 && j < CW) { ap[t] += wp[j] * vp; aq[t] += wq[j] * vq; } } }
;             __builtin_amdgcn_sched_barrier(0); }
	v_fmac_f32_e32 v138, v192, v1
	v_pk_fma_f32 v[236:237], v[116:117], v[28:29], v[236:237]
	v_fmac_f32_e32 v137, v191, v1
	v_pk_fma_f32 v[28:29], v[114:115], v[28:29], v[120:121]
	v_fma_f32 v136, v190, v1, v197
	v_lshlrev_b32_e32 v238, 16, v26
	v_and_b32_e32 v239, 0xffff0000, v26
	v_lshlrev_b32_e32 v1, 16, v135
	v_pk_fma_f32 v[38:39], v[72:73], v[238:239], v[38:39]
	v_fmac_f32_e32 v145, v169, v1
	v_pk_fma_f32 v[36:37], v[70:71], v[238:239], v[36:37]
	v_fmac_f32_e32 v144, v168, v1
	v_pk_fma_f32 v[230:231], v[68:69], v[238:239], v[230:231]
	v_fmac_f32_e32 v143, v167, v1
	v_pk_fma_f32 v[34:35], v[66:67], v[238:239], v[34:35]
	v_fmac_f32_e32 v142, v166, v1
	v_pk_fma_f32 v[232:233], v[64:65], v[238:239], v[232:233]
	v_fmac_f32_e32 v141, v196, v1
	v_pk_fma_f32 v[32:33], v[62:63], v[238:239], v[32:33]
	v_fmac_f32_e32 v140, v195, v1
	v_pk_fma_f32 v[234:235], v[60:61], v[238:239], v[234:235]
	v_fmac_f32_e32 v139, v194, v1
	v_pk_fma_f32 v[30:31], v[58:59], v[238:239], v[30:31]
	v_fmac_f32_e32 v138, v193, v1
	v_pk_fma_f32 v[236:237], v[118:119], v[238:239], v[236:237]
	v_fmac_f32_e32 v137, v192, v1
	v_pk_fma_f32 v[28:29], v[116:117], v[238:239], v[28:29]
	v_fmac_f32_e32 v136, v191, v1
	v_pk_fma_f32 v[238:239], v[114:115], v[238:239], v[120:121]
	v_fma_f32 v135, v190, v1, v197
	v_lshlrev_b32_e32 v26, 16, v27
	v_and_b32_e32 v27, 0xffff0000, v27
	v_lshlrev_b32_e32 v1, 16, v134
	v_pk_fma_f32 v[38:39], v[74:75], v[26:27], v[38:39]
	v_fmac_f32_e32 v145, v170, v1
	v_pk_fma_f32 v[36:37], v[72:73], v[26:27], v[36:37]
	v_fmac_f32_e32 v144, v169, v1
	v_pk_fma_f32 v[230:231], v[70:71], v[26:27], v[230:231]
	v_fmac_f32_e32 v143, v168, v1
	v_pk_fma_f32 v[34:35], v[68:69], v[26:27], v[34:35]
	v_fmac_f32_e32 v142, v167, v1
	v_pk_fma_f32 v[232:233], v[66:67], v[26:27], v[232:233]
	v_fmac_f32_e32 v141, v166, v1
	v_pk_fma_f32 v[32:33], v[64:65], v[26:27], v[32:33]
	v_fmac_f32_e32 v140, v196, v1
	v_pk_fma_f32 v[234:235], v[62:63], v[26:27], v[234:235]
	v_fmac_f32_e32 v139, v195, v1
	v_pk_fma_f32 v[30:31], v[60:61], v[26:27], v[30:31]
	v_fmac_f32_e32 v138, v194, v1
	v_pk_fma_f32 v[236:237], v[58:59], v[26:27], v[236:237]
	v_fmac_f32_e32 v137, v193, v1
	v_pk_fma_f32 v[28:29], v[118:119], v[26:27], v[28:29]
	v_fmac_f32_e32 v136, v192, v1
	v_pk_fma_f32 v[238:239], v[116:117], v[26:27], v[238:239]
	v_fmac_f32_e32 v135, v191, v1
	v_pk_fma_f32 v[26:27], v[114:115], v[26:27], v[120:121]
	v_fma_f32 v134, v190, v1, v197
	v_lshlrev_b32_e32 v240, 16, v24
	v_and_b32_e32 v241, 0xffff0000, v24
	v_lshlrev_b32_e32 v1, 16, v133
	v_pk_fma_f32 v[38:39], v[76:77], v[240:241], v[38:39]
	v_fmac_f32_e32 v145, v171, v1
	v_pk_fma_f32 v[36:37], v[74:75], v[240:241], v[36:37]
	v_fmac_f32_e32 v144, v170, v1
	v_pk_fma_f32 v[230:231], v[72:73], v[240:241], v[230:231]
	v_fmac_f32_e32 v143, v169, v1
	v_pk_fma_f32 v[34:35], v[70:71], v[240:241], v[34:35]
	v_fmac_f32_e32 v142, v168, v1
	v_pk_fma_f32 v[232:233], v[68:69], v[240:241], v[232:233]
	v_fmac_f32_e32 v141, v167, v1
	v_pk_fma_f32 v[32:33], v[66:67], v[240:241], v[32:33]
	v_fmac_f32_e32 v140, v166, v1
	v_pk_fma_f32 v[234:235], v[64:65], v[240:241], v[234:235]
	v_fmac_f32_e32 v139, v196, v1
	v_pk_fma_f32 v[30:31], v[62:63], v[240:241], v[30:31]
	v_fmac_f32_e32 v138, v195, v1
	v_pk_fma_f32 v[236:237], v[60:61], v[240:241], v[236:237]
	v_fmac_f32_e32 v137, v194, v1
	v_pk_fma_f32 v[28:29], v[58:59], v[240:241], v[28:29]
	v_fmac_f32_e32 v136, v193, v1
	v_pk_fma_f32 v[238:239], v[118:119], v[240:241], v[238:239]
	v_fmac_f32_e32 v135, v192, v1
	v_pk_fma_f32 v[26:27], v[116:117], v[240:241], v[26:27]
	v_fmac_f32_e32 v134, v191, v1
	v_pk_fma_f32 v[240:241], v[114:115], v[240:241], v[120:121]
	v_fma_f32 v133, v190, v1, v197
	v_lshlrev_b32_e32 v24, 16, v25
	v_and_b32_e32 v25, 0xffff0000, v25
	v_lshlrev_b32_e32 v1, 16, v5
	v_pk_fma_f32 v[38:39], v[78:79], v[24:25], v[38:39]
	v_fmac_f32_e32 v145, v172, v1
	v_pk_fma_f32 v[36:37], v[76:77], v[24:25], v[36:37]
	v_fmac_f32_e32 v144, v171, v1
	v_pk_fma_f32 v[230:231], v[74:75], v[24:25], v[230:231]
	v_fmac_f32_e32 v143, v170, v1
	v_pk_fma_f32 v[34:35], v[72:73], v[24:25], v[34:35]
	v_fmac_f32_e32 v142, v169, v1
	v_pk_fma_f32 v[232:233], v[70:71], v[24:25], v[232:233]
	v_fmac_f32_e32 v141, v168, v1
	v_pk_fma_f32 v[32:33], v[68:69], v[24:25], v[32:33]
	v_fmac_f32_e32 v140, v167, v1
	v_pk_fma_f32 v[234:235], v[66:67], v[24:25], v[234:235]
	v_fmac_f32_e32 v139, v166, v1
	v_pk_fma_f32 v[30:31], v[64:65], v[24:25], v[30:31]
	v_fmac_f32_e32 v138, v196, v1
	v_pk_fma_f32 v[236:237], v[62:63], v[24:25], v[236:237]
	v_fmac_f32_e32 v137, v195, v1
	v_pk_fma_f32 v[28:29], v[60:61], v[24:25], v[28:29]
	v_fmac_f32_e32 v136, v194, v1
	v_pk_fma_f32 v[238:239], v[58:59], v[24:25], v[238:239]
	v_fmac_f32_e32 v135, v193, v1
	v_pk_fma_f32 v[26:27], v[118:119], v[24:25], v[26:27]
	v_fmac_f32_e32 v134, v192, v1
	v_pk_fma_f32 v[240:241], v[116:117], v[24:25], v[240:241]
	v_fmac_f32_e32 v133, v191, v1
	v_pk_fma_f32 v[24:25], v[114:115], v[24:25], v[120:121]
	v_fma_f32 v5, v190, v1, v197
	v_lshlrev_b32_e32 v242, 16, v22
	v_and_b32_e32 v243, 0xffff0000, v22
	v_lshlrev_b32_e32 v1, 16, v225
	v_pk_fma_f32 v[38:39], v[80:81], v[242:243], v[38:39]
	v_fmac_f32_e32 v145, v173, v1
	v_pk_fma_f32 v[36:37], v[78:79], v[242:243], v[36:37]
	v_fmac_f32_e32 v144, v172, v1
	v_pk_fma_f32 v[230:231], v[76:77], v[242:243], v[230:231]
	v_fmac_f32_e32 v143, v171, v1
	v_pk_fma_f32 v[34:35], v[74:75], v[242:243], v[34:35]
	v_fmac_f32_e32 v142, v170, v1
	v_pk_fma_f32 v[232:233], v[72:73], v[242:243], v[232:233]
	v_fmac_f32_e32 v141, v169, v1
	v_pk_fma_f32 v[32:33], v[70:71], v[242:243], v[32:33]
	v_fmac_f32_e32 v140, v168, v1
	v_pk_fma_f32 v[234:235], v[68:69], v[242:243], v[234:235]
; #define LAS __attribute__((address_space(3)))
; __device__ __forceinline__ float bf_lo(unsigned w) { return __uint_as_float(w << 16); }
; __device__ __forceinline__ float bf_hi(unsigned w) { return __uint_as_float(w & 0xffff0000u); }
; __device__ __forceinline__ void p2_conv_unit_prompt(Frame& F, int unit, int next_pm, const ConvW& cw, size_t src_off = WS_A, size_t dst_off = WS_CACT) {
;     ...
; #pragma unroll
;         for (int rg = 0; rg < CV_ROWS; rg += 8) {
;             unsigned w2[8], w1[8];
; #pragma unroll
;             for (int i = 0; i < 8; ++i) if (rg + i < CV_ROWS) { const LAS unsigned char* rp = S + (rg + i) * (DCONV * 2) + ((rg + i) < CW - 1 ? ringLo : ringHi);
;                 w2[i] = *(const LAS unsigned*)(rp + p * 2u); w1[i] = *(const LAS unsigned short*)(rp + q * 2u); }
; #pragma unroll
;             for (int i = 0; i < 8; ++i) if (rg + i < CV_ROWS) { const int rr = rg + i; const f32x2 vp = (f32x2){bf_lo(w2[i]), bf_hi(w2[i])}; const float vq = bf_lo(w1[i]);
; #pragma unroll
;                 for (int t = 0; t < 16; ++t) { const int j = rr - t; if (j >= 0 && j < CW) { ap[t] += wp[j] * vp; aq[t] += wq[j] * vq; } } }
;             __builtin_amdgcn_sched_barrier(0); }
	v_fmac_f32_e32 v139, v167, v1
	v_pk_fma_f32 v[30:31], v[66:67], v[242:243], v[30:31]
	v_fmac_f32_e32 v138, v166, v1
	v_pk_fma_f32 v[236:237], v[64:65], v[242:243], v[236:237]
	v_fmac_f32_e32 v137, v196, v1
	v_pk_fma_f32 v[28:29], v[62:63], v[242:243], v[28:29]
	v_fmac_f32_e32 v136, v195, v1
	v_pk_fma_f32 v[238:239], v[60:61], v[242:243], v[238:239]
	v_fmac_f32_e32 v135, v194, v1
	v_pk_fma_f32 v[26:27], v[58:59], v[242:243], v[26:27]
	v_fmac_f32_e32 v134, v193, v1
	v_pk_fma_f32 v[240:241], v[118:119], v[242:243], v[240:241]
	v_fmac_f32_e32 v133, v192, v1
	v_pk_fma_f32 v[24:25], v[116:117], v[242:243], v[24:25]
	v_fmac_f32_e32 v5, v191, v1
	v_pk_fma_f32 v[242:243], v[114:115], v[242:243], v[120:121]
	v_fma_f32 v2, v190, v1, v197
	v_lshlrev_b32_e32 v22, 16, v23
	v_and_b32_e32 v23, 0xffff0000, v23
	v_lshlrev_b32_e32 v1, 16, v7
	v_pk_fma_f32 v[38:39], v[82:83], v[22:23], v[38:39]
	v_fmac_f32_e32 v145, v174, v1
	v_pk_fma_f32 v[36:37], v[80:81], v[22:23], v[36:37]
	v_fmac_f32_e32 v144, v173, v1
	v_pk_fma_f32 v[230:231], v[78:79], v[22:23], v[230:231]
	v_fmac_f32_e32 v143, v172, v1
	v_pk_fma_f32 v[34:35], v[76:77], v[22:23], v[34:35]
	v_fmac_f32_e32 v142, v171, v1
	v_pk_fma_f32 v[232:233], v[74:75], v[22:23], v[232:233]
	v_fmac_f32_e32 v141, v170, v1
	v_pk_fma_f32 v[32:33], v[72:73], v[22:23], v[32:33]
	v_fmac_f32_e32 v140, v169, v1
	v_pk_fma_f32 v[234:235], v[70:71], v[22:23], v[234:235]
	v_fmac_f32_e32 v139, v168, v1
	v_pk_fma_f32 v[30:31], v[68:69], v[22:23], v[30:31]
	v_fmac_f32_e32 v138, v167, v1
	v_pk_fma_f32 v[236:237], v[66:67], v[22:23], v[236:237]
	v_fmac_f32_e32 v137, v166, v1
	v_pk_fma_f32 v[28:29], v[64:65], v[22:23], v[28:29]
	v_fmac_f32_e32 v136, v196, v1
	v_pk_fma_f32 v[238:239], v[62:63], v[22:23], v[238:239]
	v_fmac_f32_e32 v135, v195, v1
	v_pk_fma_f32 v[26:27], v[60:61], v[22:23], v[26:27]
	v_fmac_f32_e32 v134, v194, v1
	v_pk_fma_f32 v[240:241], v[58:59], v[22:23], v[240:241]
	v_fmac_f32_e32 v133, v193, v1
	v_pk_fma_f32 v[24:25], v[118:119], v[22:23], v[24:25]
	v_fmac_f32_e32 v5, v192, v1
	v_pk_fma_f32 v[242:243], v[116:117], v[22:23], v[242:243]
	v_fmac_f32_e32 v2, v191, v1
	v_pk_fma_f32 v[22:23], v[114:115], v[22:23], v[120:121]
	v_fma_f32 v7, v190, v1, v197
	v_lshlrev_b32_e32 v244, 16, v20
	v_and_b32_e32 v245, 0xffff0000, v20
	v_lshlrev_b32_e32 v1, 16, v224
	v_pk_fma_f32 v[38:39], v[84:85], v[244:245], v[38:39]
	v_fmac_f32_e32 v145, v175, v1
	v_pk_fma_f32 v[36:37], v[82:83], v[244:245], v[36:37]
	v_fmac_f32_e32 v144, v174, v1
	v_pk_fma_f32 v[224:225], v[80:81], v[244:245], v[230:231]
	v_fmac_f32_e32 v143, v173, v1
	v_pk_fma_f32 v[34:35], v[78:79], v[244:245], v[34:35]
	v_fmac_f32_e32 v142, v172, v1
	v_pk_fma_f32 v[230:231], v[76:77], v[244:245], v[232:233]
	v_fmac_f32_e32 v141, v171, v1
	v_pk_fma_f32 v[32:33], v[74:75], v[244:245], v[32:33]
	v_fmac_f32_e32 v140, v170, v1
	v_pk_fma_f32 v[232:233], v[72:73], v[244:245], v[234:235]
	v_fmac_f32_e32 v139, v169, v1
	v_pk_fma_f32 v[30:31], v[70:71], v[244:245], v[30:31]
	v_fmac_f32_e32 v138, v168, v1
	v_pk_fma_f32 v[234:235], v[68:69], v[244:245], v[236:237]
	v_fmac_f32_e32 v137, v167, v1
	v_pk_fma_f32 v[28:29], v[66:67], v[244:245], v[28:29]
	v_fmac_f32_e32 v136, v166, v1
	v_pk_fma_f32 v[236:237], v[64:65], v[244:245], v[238:239]
	v_fmac_f32_e32 v135, v196, v1
	v_pk_fma_f32 v[26:27], v[62:63], v[244:245], v[26:27]
	v_fmac_f32_e32 v134, v195, v1
	v_pk_fma_f32 v[238:239], v[60:61], v[244:245], v[240:241]
	v_fmac_f32_e32 v133, v194, v1
	v_pk_fma_f32 v[24:25], v[58:59], v[244:245], v[24:25]
	v_fmac_f32_e32 v5, v193, v1
	v_pk_fma_f32 v[240:241], v[118:119], v[244:245], v[242:243]
	v_fmac_f32_e32 v2, v192, v1
	v_pk_fma_f32 v[22:23], v[116:117], v[244:245], v[22:23]
	v_fmac_f32_e32 v7, v191, v1
	v_lshlrev_b32_e32 v20, 16, v21
	v_and_b32_e32 v21, 0xffff0000, v21
	v_lshlrev_b32_e32 v1, 16, v223
	v_pk_fma_f32 v[38:39], v[86:87], v[20:21], v[38:39]
	v_fmac_f32_e32 v145, v176, v1
	v_pk_fma_f32 v[36:37], v[84:85], v[20:21], v[36:37]
	v_fmac_f32_e32 v144, v175, v1
	v_pk_fma_f32 v[224:225], v[82:83], v[20:21], v[224:225]
	v_fmac_f32_e32 v143, v174, v1
	v_pk_fma_f32 v[34:35], v[80:81], v[20:21], v[34:35]
	v_fmac_f32_e32 v142, v173, v1
	v_pk_fma_f32 v[230:231], v[78:79], v[20:21], v[230:231]
	v_fmac_f32_e32 v141, v172, v1
	v_pk_fma_f32 v[32:33], v[76:77], v[20:21], v[32:33]
	v_fmac_f32_e32 v140, v171, v1
	v_pk_fma_f32 v[232:233], v[74:75], v[20:21], v[232:233]
	v_fmac_f32_e32 v139, v170, v1
	v_pk_fma_f32 v[30:31], v[72:73], v[20:21], v[30:31]
	v_fmac_f32_e32 v138, v169, v1
	v_pk_fma_f32 v[234:235], v[70:71], v[20:21], v[234:235]
	v_fmac_f32_e32 v137, v168, v1
	v_pk_fma_f32 v[28:29], v[68:69], v[20:21], v[28:29]
	v_fmac_f32_e32 v136, v167, v1
	v_pk_fma_f32 v[236:237], v[66:67], v[20:21], v[236:237]
	v_fmac_f32_e32 v135, v166, v1
	v_pk_fma_f32 v[26:27], v[64:65], v[20:21], v[26:27]
	v_fmac_f32_e32 v134, v196, v1
	v_pk_fma_f32 v[238:239], v[62:63], v[20:21], v[238:239]
	v_fmac_f32_e32 v133, v195, v1
	v_pk_fma_f32 v[24:25], v[60:61], v[20:21], v[24:25]
	v_fmac_f32_e32 v5, v194, v1
	v_pk_fma_f32 v[240:241], v[58:59], v[20:21], v[240:241]
	v_fmac_f32_e32 v2, v193, v1
	v_pk_fma_f32 v[20:21], v[118:119], v[20:21], v[22:23]
	v_fmac_f32_e32 v7, v192, v1
	v_lshlrev_b32_e32 v22, 16, v18
	v_and_b32_e32 v23, 0xffff0000, v18
	v_lshlrev_b32_e32 v1, 16, v222
	v_pk_fma_f32 v[38:39], v[88:89], v[22:23], v[38:39]
	v_fmac_f32_e32 v145, v177, v1
	v_pk_fma_f32 v[36:37], v[86:87], v[22:23], v[36:37]
	v_fmac_f32_e32 v144, v176, v1
	v_pk_fma_f32 v[222:223], v[84:85], v[22:23], v[224:225]
	v_fmac_f32_e32 v143, v175, v1
	v_pk_fma_f32 v[34:35], v[82:83], v[22:23], v[34:35]
	v_fmac_f32_e32 v142, v174, v1
; #define LAS __attribute__((address_space(3)))
; __device__ __forceinline__ float bf_lo(unsigned w) { return __uint_as_float(w << 16); }
; __device__ __forceinline__ float bf_hi(unsigned w) { return __uint_as_float(w & 0xffff0000u); }
; __device__ __forceinline__ void p2_conv_unit_prompt(Frame& F, int unit, int next_pm, const ConvW& cw, size_t src_off = WS_A, size_t dst_off = WS_CACT) {
;     ...
; #pragma unroll
;         for (int rg = 0; rg < CV_ROWS; rg += 8) {
;             unsigned w2[8], w1[8];
; #pragma unroll
;             for (int i = 0; i < 8; ++i) if (rg + i < CV_ROWS) { const LAS unsigned char* rp = S + (rg + i) * (DCONV * 2) + ((rg + i) < CW - 1 ? ringLo : ringHi);
;                 w2[i] = *(const LAS unsigned*)(rp + p * 2u); w1[i] = *(const LAS unsigned short*)(rp + q * 2u); }
; #pragma unroll
;             for (int i = 0; i < 8; ++i) if (rg + i < CV_ROWS) { const int rr = rg + i; const f32x2 vp = (f32x2){bf_lo(w2[i]), bf_hi(w2[i])}; const float vq = bf_lo(w1[i]);
; #pragma unroll
;                 for (int t = 0; t < 16; ++t) { const int j = rr - t; if (j >= 0 && j < CW) { ap[t] += wp[j] * vp; aq[t] += wq[j] * vq; } } }
;             __builtin_amdgcn_sched_barrier(0); }
	v_pk_fma_f32 v[224:225], v[80:81], v[22:23], v[230:231]
	v_fmac_f32_e32 v141, v173, v1
	v_pk_fma_f32 v[32:33], v[78:79], v[22:23], v[32:33]
	v_fmac_f32_e32 v140, v172, v1
	v_pk_fma_f32 v[230:231], v[76:77], v[22:23], v[232:233]
	v_fmac_f32_e32 v139, v171, v1
	v_pk_fma_f32 v[30:31], v[74:75], v[22:23], v[30:31]
	v_fmac_f32_e32 v138, v170, v1
	v_pk_fma_f32 v[232:233], v[72:73], v[22:23], v[234:235]
	v_fmac_f32_e32 v137, v169, v1
	v_pk_fma_f32 v[28:29], v[70:71], v[22:23], v[28:29]
	v_fmac_f32_e32 v136, v168, v1
	v_pk_fma_f32 v[234:235], v[68:69], v[22:23], v[236:237]
	v_fmac_f32_e32 v135, v167, v1
	v_pk_fma_f32 v[26:27], v[66:67], v[22:23], v[26:27]
	v_fmac_f32_e32 v134, v166, v1
	v_pk_fma_f32 v[236:237], v[64:65], v[22:23], v[238:239]
	v_fmac_f32_e32 v133, v196, v1
	v_pk_fma_f32 v[24:25], v[62:63], v[22:23], v[24:25]
	v_fmac_f32_e32 v5, v195, v1
	v_pk_fma_f32 v[238:239], v[60:61], v[22:23], v[240:241]
	v_fmac_f32_e32 v2, v194, v1
	v_pk_fma_f32 v[20:21], v[58:59], v[22:23], v[20:21]
	v_fmac_f32_e32 v7, v193, v1
	v_lshlrev_b32_e32 v18, 16, v19
	v_and_b32_e32 v19, 0xffff0000, v19
	v_lshlrev_b32_e32 v1, 16, v221
	v_pk_fma_f32 v[22:23], v[90:91], v[18:19], v[38:39]
	v_fmac_f32_e32 v145, v178, v1
	v_pk_fma_f32 v[36:37], v[88:89], v[18:19], v[36:37]
	v_fmac_f32_e32 v144, v177, v1
	v_pk_fma_f32 v[38:39], v[86:87], v[18:19], v[222:223]
	v_fmac_f32_e32 v143, v176, v1
	v_pk_fma_f32 v[34:35], v[84:85], v[18:19], v[34:35]
	v_fmac_f32_e32 v142, v175, v1
	v_pk_fma_f32 v[222:223], v[82:83], v[18:19], v[224:225]
	v_fmac_f32_e32 v141, v174, v1
	v_pk_fma_f32 v[32:33], v[80:81], v[18:19], v[32:33]
	v_fmac_f32_e32 v140, v173, v1
	v_pk_fma_f32 v[224:225], v[78:79], v[18:19], v[230:231]
	v_fmac_f32_e32 v139, v172, v1
	v_pk_fma_f32 v[30:31], v[76:77], v[18:19], v[30:31]
	v_fmac_f32_e32 v138, v171, v1
	v_pk_fma_f32 v[230:231], v[74:75], v[18:19], v[232:233]
	v_fmac_f32_e32 v137, v170, v1
	v_pk_fma_f32 v[28:29], v[72:73], v[18:19], v[28:29]
	v_fmac_f32_e32 v136, v169, v1
	v_pk_fma_f32 v[232:233], v[70:71], v[18:19], v[234:235]
	v_fmac_f32_e32 v135, v168, v1
	v_pk_fma_f32 v[26:27], v[68:69], v[18:19], v[26:27]
	v_fmac_f32_e32 v134, v167, v1
	v_pk_fma_f32 v[234:235], v[66:67], v[18:19], v[236:237]
	v_fmac_f32_e32 v133, v166, v1
	v_pk_fma_f32 v[24:25], v[64:65], v[18:19], v[24:25]
	v_fmac_f32_e32 v5, v196, v1
	v_pk_fma_f32 v[236:237], v[62:63], v[18:19], v[238:239]
	v_fmac_f32_e32 v2, v195, v1
	v_pk_fma_f32 v[18:19], v[60:61], v[18:19], v[20:21]
	v_fmac_f32_e32 v7, v194, v1
	v_lshlrev_b32_e32 v20, 16, v16
	v_and_b32_e32 v21, 0xffff0000, v16
	v_lshlrev_b32_e32 v1, 16, v220
	v_pk_fma_f32 v[22:23], v[92:93], v[20:21], v[22:23]
	v_fmac_f32_e32 v145, v179, v1
	v_pk_fma_f32 v[36:37], v[90:91], v[20:21], v[36:37]
	v_fmac_f32_e32 v144, v178, v1
	v_pk_fma_f32 v[38:39], v[88:89], v[20:21], v[38:39]
	v_fmac_f32_e32 v143, v177, v1
	v_pk_fma_f32 v[34:35], v[86:87], v[20:21], v[34:35]
	v_fmac_f32_e32 v142, v176, v1
	v_pk_fma_f32 v[220:221], v[84:85], v[20:21], v[222:223]
	v_fmac_f32_e32 v141, v175, v1
	v_pk_fma_f32 v[32:33], v[82:83], v[20:21], v[32:33]
	v_fmac_f32_e32 v140, v174, v1
	v_pk_fma_f32 v[222:223], v[80:81], v[20:21], v[224:225]
	v_fmac_f32_e32 v139, v173, v1
	v_pk_fma_f32 v[30:31], v[78:79], v[20:21], v[30:31]
	v_fmac_f32_e32 v138, v172, v1
	v_pk_fma_f32 v[224:225], v[76:77], v[20:21], v[230:231]
	v_fmac_f32_e32 v137, v171, v1
	v_pk_fma_f32 v[28:29], v[74:75], v[20:21], v[28:29]
	v_fmac_f32_e32 v136, v170, v1
	v_pk_fma_f32 v[230:231], v[72:73], v[20:21], v[232:233]
	v_fmac_f32_e32 v135, v169, v1
	v_pk_fma_f32 v[26:27], v[70:71], v[20:21], v[26:27]
	v_fmac_f32_e32 v134, v168, v1
	v_pk_fma_f32 v[232:233], v[68:69], v[20:21], v[234:235]
	v_fmac_f32_e32 v133, v167, v1
	v_pk_fma_f32 v[24:25], v[66:67], v[20:21], v[24:25]
	v_fmac_f32_e32 v5, v166, v1
	v_pk_fma_f32 v[234:235], v[64:65], v[20:21], v[236:237]
	v_fmac_f32_e32 v2, v196, v1
	v_pk_fma_f32 v[18:19], v[62:63], v[20:21], v[18:19]
	v_fmac_f32_e32 v7, v195, v1
	v_lshlrev_b32_e32 v16, 16, v17
	v_and_b32_e32 v17, 0xffff0000, v17
	v_lshlrev_b32_e32 v1, 16, v219
	v_pk_fma_f32 v[20:21], v[94:95], v[16:17], v[22:23]
	v_fmac_f32_e32 v145, v180, v1
	v_pk_fma_f32 v[22:23], v[92:93], v[16:17], v[36:37]
	v_fmac_f32_e32 v144, v179, v1
	v_pk_fma_f32 v[36:37], v[90:91], v[16:17], v[38:39]
	v_fmac_f32_e32 v143, v178, v1
	v_pk_fma_f32 v[34:35], v[88:89], v[16:17], v[34:35]
	v_fmac_f32_e32 v142, v177, v1
	v_pk_fma_f32 v[38:39], v[86:87], v[16:17], v[220:221]
	v_fmac_f32_e32 v141, v176, v1
	v_pk_fma_f32 v[32:33], v[84:85], v[16:17], v[32:33]
	v_fmac_f32_e32 v140, v175, v1
	v_pk_fma_f32 v[220:221], v[82:83], v[16:17], v[222:223]
	v_fmac_f32_e32 v139, v174, v1
	v_pk_fma_f32 v[30:31], v[80:81], v[16:17], v[30:31]
	v_fmac_f32_e32 v138, v173, v1
	v_pk_fma_f32 v[222:223], v[78:79], v[16:17], v[224:225]
	v_fmac_f32_e32 v137, v172, v1
	v_pk_fma_f32 v[28:29], v[76:77], v[16:17], v[28:29]
	v_fmac_f32_e32 v136, v171, v1
	v_pk_fma_f32 v[224:225], v[74:75], v[16:17], v[230:231]
	v_fmac_f32_e32 v135, v170, v1
	v_pk_fma_f32 v[26:27], v[72:73], v[16:17], v[26:27]
	v_fmac_f32_e32 v134, v169, v1
	v_pk_fma_f32 v[230:231], v[70:71], v[16:17], v[232:233]
	v_fmac_f32_e32 v133, v168, v1
	v_pk_fma_f32 v[24:25], v[68:69], v[16:17], v[24:25]
	v_fmac_f32_e32 v5, v167, v1
	v_pk_fma_f32 v[232:233], v[66:67], v[16:17], v[234:235]
	v_fmac_f32_e32 v2, v166, v1
	v_pk_fma_f32 v[16:17], v[64:65], v[16:17], v[18:19]
	v_fmac_f32_e32 v7, v196, v1
	v_lshlrev_b32_e32 v18, 16, v218
	v_and_b32_e32 v19, 0xffff0000, v218
	v_lshlrev_b32_e32 v1, 16, v217
	v_pk_fma_f32 v[20:21], v[96:97], v[18:19], v[20:21]
	v_fmac_f32_e32 v145, v181, v1
	v_pk_fma_f32 v[22:23], v[94:95], v[18:19], v[22:23]
; #define LAS __attribute__((address_space(3)))
; __device__ __forceinline__ float bf_lo(unsigned w) { return __uint_as_float(w << 16); }
; __device__ __forceinline__ float bf_hi(unsigned w) { return __uint_as_float(w & 0xffff0000u); }
; __device__ __forceinline__ void p2_conv_unit_prompt(Frame& F, int unit, int next_pm, const ConvW& cw, size_t src_off = WS_A, size_t dst_off = WS_CACT) {
;     ...
; #pragma unroll
;         for (int rg = 0; rg < CV_ROWS; rg += 8) {
;             unsigned w2[8], w1[8];
; #pragma unroll
;             for (int i = 0; i < 8; ++i) if (rg + i < CV_ROWS) { const LAS unsigned char* rp = S + (rg + i) * (DCONV * 2) + ((rg + i) < CW - 1 ? ringLo : ringHi);
;                 w2[i] = *(const LAS unsigned*)(rp + p * 2u); w1[i] = *(const LAS unsigned short*)(rp + q * 2u); }
; #pragma unroll
;             for (int i = 0; i < 8; ++i) if (rg + i < CV_ROWS) { const int rr = rg + i; const f32x2 vp = (f32x2){bf_lo(w2[i]), bf_hi(w2[i])}; const float vq = bf_lo(w1[i]);
; #pragma unroll
;                 for (int t = 0; t < 16; ++t) { const int j = rr - t; if (j >= 0 && j < CW) { ap[t] += wp[j] * vp; aq[t] += wq[j] * vq; } } }
;             __builtin_amdgcn_sched_barrier(0); }
	v_fmac_f32_e32 v144, v180, v1
	v_pk_fma_f32 v[36:37], v[92:93], v[18:19], v[36:37]
	v_fmac_f32_e32 v143, v179, v1
	v_pk_fma_f32 v[34:35], v[90:91], v[18:19], v[34:35]
	v_fmac_f32_e32 v142, v178, v1
	v_pk_fma_f32 v[38:39], v[88:89], v[18:19], v[38:39]
	v_fmac_f32_e32 v141, v177, v1
	v_pk_fma_f32 v[32:33], v[86:87], v[18:19], v[32:33]
	v_fmac_f32_e32 v140, v176, v1
	v_pk_fma_f32 v[218:219], v[84:85], v[18:19], v[220:221]
	v_fmac_f32_e32 v139, v175, v1
	v_pk_fma_f32 v[30:31], v[82:83], v[18:19], v[30:31]
	v_fmac_f32_e32 v138, v174, v1
	v_pk_fma_f32 v[220:221], v[80:81], v[18:19], v[222:223]
	v_fmac_f32_e32 v137, v173, v1
	v_pk_fma_f32 v[28:29], v[78:79], v[18:19], v[28:29]
	v_fmac_f32_e32 v136, v172, v1
	v_pk_fma_f32 v[222:223], v[76:77], v[18:19], v[224:225]
	v_fmac_f32_e32 v135, v171, v1
	v_pk_fma_f32 v[26:27], v[74:75], v[18:19], v[26:27]
	v_fmac_f32_e32 v134, v170, v1
	v_pk_fma_f32 v[224:225], v[72:73], v[18:19], v[230:231]
	v_fmac_f32_e32 v133, v169, v1
	v_pk_fma_f32 v[24:25], v[70:71], v[18:19], v[24:25]
	v_fmac_f32_e32 v5, v168, v1
	v_pk_fma_f32 v[230:231], v[68:69], v[18:19], v[232:233]
	v_fmac_f32_e32 v2, v167, v1
	v_pk_fma_f32 v[16:17], v[66:67], v[18:19], v[16:17]
	v_fmac_f32_e32 v7, v166, v1
	v_lshlrev_b32_e32 v18, 16, v216
	v_and_b32_e32 v19, 0xffff0000, v216
	v_lshlrev_b32_e32 v1, 16, v215
	v_pk_fma_f32 v[20:21], v[98:99], v[18:19], v[20:21]
	v_fmac_f32_e32 v145, v182, v1
	v_pk_fma_f32 v[22:23], v[96:97], v[18:19], v[22:23]
	v_fmac_f32_e32 v144, v181, v1
	v_pk_fma_f32 v[36:37], v[94:95], v[18:19], v[36:37]
	v_fmac_f32_e32 v143, v180, v1
	v_pk_fma_f32 v[34:35], v[92:93], v[18:19], v[34:35]
	v_fmac_f32_e32 v142, v179, v1
	v_pk_fma_f32 v[38:39], v[90:91], v[18:19], v[38:39]
	v_fmac_f32_e32 v141, v178, v1
	v_pk_fma_f32 v[32:33], v[88:89], v[18:19], v[32:33]
	v_fmac_f32_e32 v140, v177, v1
	v_pk_fma_f32 v[214:215], v[86:87], v[18:19], v[218:219]
	v_fmac_f32_e32 v139, v176, v1
	v_pk_fma_f32 v[30:31], v[84:85], v[18:19], v[30:31]
	v_fmac_f32_e32 v138, v175, v1
	v_pk_fma_f32 v[216:217], v[82:83], v[18:19], v[220:221]
	v_fmac_f32_e32 v137, v174, v1
	v_pk_fma_f32 v[28:29], v[80:81], v[18:19], v[28:29]
	v_fmac_f32_e32 v136, v173, v1
	v_pk_fma_f32 v[218:219], v[78:79], v[18:19], v[222:223]
	v_fmac_f32_e32 v135, v172, v1
	v_pk_fma_f32 v[26:27], v[76:77], v[18:19], v[26:27]
	v_fmac_f32_e32 v134, v171, v1
	v_pk_fma_f32 v[220:221], v[74:75], v[18:19], v[224:225]
	v_fmac_f32_e32 v133, v170, v1
	v_pk_fma_f32 v[24:25], v[72:73], v[18:19], v[24:25]
	v_fmac_f32_e32 v5, v169, v1
	v_pk_fma_f32 v[222:223], v[70:71], v[18:19], v[230:231]
	v_fmac_f32_e32 v2, v168, v1
	v_pk_fma_f32 v[16:17], v[68:69], v[18:19], v[16:17]
	v_fmac_f32_e32 v7, v167, v1
	v_lshlrev_b32_e32 v18, 16, v213
	v_and_b32_e32 v19, 0xffff0000, v213
	v_lshlrev_b32_e32 v1, 16, v212
	v_pk_fma_f32 v[20:21], v[100:101], v[18:19], v[20:21]
	v_fmac_f32_e32 v145, v183, v1
	v_pk_fma_f32 v[22:23], v[98:99], v[18:19], v[22:23]
	v_fmac_f32_e32 v144, v182, v1
	v_pk_fma_f32 v[36:37], v[96:97], v[18:19], v[36:37]
	v_fmac_f32_e32 v143, v181, v1
	v_pk_fma_f32 v[34:35], v[94:95], v[18:19], v[34:35]
	v_fmac_f32_e32 v142, v180, v1
	v_pk_fma_f32 v[38:39], v[92:93], v[18:19], v[38:39]
	v_fmac_f32_e32 v141, v179, v1
	v_pk_fma_f32 v[32:33], v[90:91], v[18:19], v[32:33]
	v_fmac_f32_e32 v140, v178, v1
	v_pk_fma_f32 v[212:213], v[88:89], v[18:19], v[214:215]
	v_fmac_f32_e32 v139, v177, v1
	v_pk_fma_f32 v[30:31], v[86:87], v[18:19], v[30:31]
	v_fmac_f32_e32 v138, v176, v1
	v_pk_fma_f32 v[214:215], v[84:85], v[18:19], v[216:217]
	v_fmac_f32_e32 v137, v175, v1
	v_pk_fma_f32 v[28:29], v[82:83], v[18:19], v[28:29]
	v_fmac_f32_e32 v136, v174, v1
	v_pk_fma_f32 v[216:217], v[80:81], v[18:19], v[218:219]
	v_fmac_f32_e32 v135, v173, v1
	v_pk_fma_f32 v[26:27], v[78:79], v[18:19], v[26:27]
	v_fmac_f32_e32 v134, v172, v1
	v_pk_fma_f32 v[218:219], v[76:77], v[18:19], v[220:221]
	v_fmac_f32_e32 v133, v171, v1
	v_pk_fma_f32 v[24:25], v[74:75], v[18:19], v[24:25]
	v_fmac_f32_e32 v5, v170, v1
	v_pk_fma_f32 v[220:221], v[72:73], v[18:19], v[222:223]
	v_fmac_f32_e32 v2, v169, v1
	v_pk_fma_f32 v[16:17], v[70:71], v[18:19], v[16:17]
	v_fmac_f32_e32 v7, v168, v1
	v_lshlrev_b32_e32 v18, 16, v211
	v_and_b32_e32 v19, 0xffff0000, v211
	v_lshlrev_b32_e32 v1, 16, v210
	v_pk_fma_f32 v[20:21], v[102:103], v[18:19], v[20:21]
	v_fmac_f32_e32 v145, v184, v1
	v_pk_fma_f32 v[22:23], v[100:101], v[18:19], v[22:23]
	v_fmac_f32_e32 v144, v183, v1
	v_pk_fma_f32 v[36:37], v[98:99], v[18:19], v[36:37]
	v_fmac_f32_e32 v143, v182, v1
	v_pk_fma_f32 v[34:35], v[96:97], v[18:19], v[34:35]
	v_fmac_f32_e32 v142, v181, v1
	v_pk_fma_f32 v[38:39], v[94:95], v[18:19], v[38:39]
	v_fmac_f32_e32 v141, v180, v1
	v_pk_fma_f32 v[32:33], v[92:93], v[18:19], v[32:33]
	v_fmac_f32_e32 v140, v179, v1
	v_pk_fma_f32 v[210:211], v[90:91], v[18:19], v[212:213]
	v_fmac_f32_e32 v139, v178, v1
	v_pk_fma_f32 v[30:31], v[88:89], v[18:19], v[30:31]
	v_fmac_f32_e32 v138, v177, v1
	v_pk_fma_f32 v[212:213], v[86:87], v[18:19], v[214:215]
	v_fmac_f32_e32 v137, v176, v1
	v_pk_fma_f32 v[28:29], v[84:85], v[18:19], v[28:29]
	v_fmac_f32_e32 v136, v175, v1
	v_pk_fma_f32 v[214:215], v[82:83], v[18:19], v[216:217]
	v_fmac_f32_e32 v135, v174, v1
	v_pk_fma_f32 v[26:27], v[80:81], v[18:19], v[26:27]
	v_fmac_f32_e32 v134, v173, v1
	v_pk_fma_f32 v[216:217], v[78:79], v[18:19], v[218:219]
	v_fmac_f32_e32 v133, v172, v1
	v_pk_fma_f32 v[24:25], v[76:77], v[18:19], v[24:25]
	v_fmac_f32_e32 v5, v171, v1
	v_pk_fma_f32 v[218:219], v[74:75], v[18:19], v[220:221]
	v_fmac_f32_e32 v2, v170, v1
	v_pk_fma_f32 v[16:17], v[72:73], v[18:19], v[16:17]
	v_fmac_f32_e32 v7, v169, v1
	v_lshlrev_b32_e32 v18, 16, v209
; #define LAS __attribute__((address_space(3)))
; __device__ __forceinline__ float bf_lo(unsigned w) { return __uint_as_float(w << 16); }
; __device__ __forceinline__ float bf_hi(unsigned w) { return __uint_as_float(w & 0xffff0000u); }
; __device__ __forceinline__ void p2_conv_unit_prompt(Frame& F, int unit, int next_pm, const ConvW& cw, size_t src_off = WS_A, size_t dst_off = WS_CACT) {
;     ...
; #pragma unroll
;         for (int rg = 0; rg < CV_ROWS; rg += 8) {
;             unsigned w2[8], w1[8];
; #pragma unroll
;             for (int i = 0; i < 8; ++i) if (rg + i < CV_ROWS) { const LAS unsigned char* rp = S + (rg + i) * (DCONV * 2) + ((rg + i) < CW - 1 ? ringLo : ringHi);
;                 w2[i] = *(const LAS unsigned*)(rp + p * 2u); w1[i] = *(const LAS unsigned short*)(rp + q * 2u); }
; #pragma unroll
;             for (int i = 0; i < 8; ++i) if (rg + i < CV_ROWS) { const int rr = rg + i; const f32x2 vp = (f32x2){bf_lo(w2[i]), bf_hi(w2[i])}; const float vq = bf_lo(w1[i]);
; #pragma unroll
;                 for (int t = 0; t < 16; ++t) { const int j = rr - t; if (j >= 0 && j < CW) { ap[t] += wp[j] * vp; aq[t] += wq[j] * vq; } } }
;             __builtin_amdgcn_sched_barrier(0); }
	v_and_b32_e32 v19, 0xffff0000, v209
	v_lshlrev_b32_e32 v1, 16, v208
	v_pk_fma_f32 v[20:21], v[104:105], v[18:19], v[20:21]
	v_fmac_f32_e32 v145, v185, v1
	v_pk_fma_f32 v[22:23], v[102:103], v[18:19], v[22:23]
	v_fmac_f32_e32 v144, v184, v1
	v_pk_fma_f32 v[36:37], v[100:101], v[18:19], v[36:37]
	v_fmac_f32_e32 v143, v183, v1
	v_pk_fma_f32 v[34:35], v[98:99], v[18:19], v[34:35]
	v_fmac_f32_e32 v142, v182, v1
	v_pk_fma_f32 v[38:39], v[96:97], v[18:19], v[38:39]
	v_fmac_f32_e32 v141, v181, v1
	v_pk_fma_f32 v[32:33], v[94:95], v[18:19], v[32:33]
	v_fmac_f32_e32 v140, v180, v1
	v_pk_fma_f32 v[208:209], v[92:93], v[18:19], v[210:211]
	v_fmac_f32_e32 v139, v179, v1
	v_pk_fma_f32 v[30:31], v[90:91], v[18:19], v[30:31]
	v_fmac_f32_e32 v138, v178, v1
	v_pk_fma_f32 v[210:211], v[88:89], v[18:19], v[212:213]
	v_fmac_f32_e32 v137, v177, v1
	v_pk_fma_f32 v[28:29], v[86:87], v[18:19], v[28:29]
	v_fmac_f32_e32 v136, v176, v1
	v_pk_fma_f32 v[212:213], v[84:85], v[18:19], v[214:215]
	v_fmac_f32_e32 v135, v175, v1
	v_pk_fma_f32 v[26:27], v[82:83], v[18:19], v[26:27]
	v_fmac_f32_e32 v134, v174, v1
	v_pk_fma_f32 v[214:215], v[80:81], v[18:19], v[216:217]
	v_fmac_f32_e32 v133, v173, v1
	v_pk_fma_f32 v[24:25], v[78:79], v[18:19], v[24:25]
	v_fmac_f32_e32 v5, v172, v1
	v_pk_fma_f32 v[216:217], v[76:77], v[18:19], v[218:219]
	v_fmac_f32_e32 v2, v171, v1
	v_pk_fma_f32 v[16:17], v[74:75], v[18:19], v[16:17]
	v_fmac_f32_e32 v7, v170, v1
	v_lshlrev_b32_e32 v18, 16, v207
	v_and_b32_e32 v19, 0xffff0000, v207
	v_lshlrev_b32_e32 v1, 16, v206
	v_pk_fma_f32 v[20:21], v[106:107], v[18:19], v[20:21]
	v_fmac_f32_e32 v145, v186, v1
	v_pk_fma_f32 v[22:23], v[104:105], v[18:19], v[22:23]
	v_fmac_f32_e32 v144, v185, v1
	v_pk_fma_f32 v[36:37], v[102:103], v[18:19], v[36:37]
	v_fmac_f32_e32 v143, v184, v1
	v_pk_fma_f32 v[34:35], v[100:101], v[18:19], v[34:35]
	v_fmac_f32_e32 v142, v183, v1
	v_pk_fma_f32 v[38:39], v[98:99], v[18:19], v[38:39]
	v_fmac_f32_e32 v141, v182, v1
	v_pk_fma_f32 v[32:33], v[96:97], v[18:19], v[32:33]
	v_fmac_f32_e32 v140, v181, v1
	v_pk_fma_f32 v[206:207], v[94:95], v[18:19], v[208:209]
	v_fmac_f32_e32 v139, v180, v1
	v_pk_fma_f32 v[30:31], v[92:93], v[18:19], v[30:31]
	v_fmac_f32_e32 v138, v179, v1
	v_pk_fma_f32 v[208:209], v[90:91], v[18:19], v[210:211]
	v_fmac_f32_e32 v137, v178, v1
	v_pk_fma_f32 v[28:29], v[88:89], v[18:19], v[28:29]
	v_fmac_f32_e32 v136, v177, v1
	v_pk_fma_f32 v[210:211], v[86:87], v[18:19], v[212:213]
	v_fmac_f32_e32 v135, v176, v1
	v_pk_fma_f32 v[26:27], v[84:85], v[18:19], v[26:27]
	v_fmac_f32_e32 v134, v175, v1
	v_pk_fma_f32 v[212:213], v[82:83], v[18:19], v[214:215]
	v_fmac_f32_e32 v133, v174, v1
	v_pk_fma_f32 v[24:25], v[80:81], v[18:19], v[24:25]
	v_fmac_f32_e32 v5, v173, v1
	v_pk_fma_f32 v[214:215], v[78:79], v[18:19], v[216:217]
	v_fmac_f32_e32 v2, v172, v1
	v_pk_fma_f32 v[16:17], v[76:77], v[18:19], v[16:17]
	v_fmac_f32_e32 v7, v171, v1
	v_lshlrev_b32_e32 v18, 16, v205
	v_and_b32_e32 v19, 0xffff0000, v205
	v_lshlrev_b32_e32 v1, 16, v204
	v_pk_fma_f32 v[20:21], v[108:109], v[18:19], v[20:21]
	v_fmac_f32_e32 v145, v187, v1
	v_pk_fma_f32 v[22:23], v[106:107], v[18:19], v[22:23]
	v_fmac_f32_e32 v144, v186, v1
	v_pk_fma_f32 v[36:37], v[104:105], v[18:19], v[36:37]
	v_fmac_f32_e32 v143, v185, v1
	v_pk_fma_f32 v[34:35], v[102:103], v[18:19], v[34:35]
	v_fmac_f32_e32 v142, v184, v1
	v_pk_fma_f32 v[38:39], v[100:101], v[18:19], v[38:39]
	v_fmac_f32_e32 v141, v183, v1
	v_pk_fma_f32 v[32:33], v[98:99], v[18:19], v[32:33]
	v_fmac_f32_e32 v140, v182, v1
	v_pk_fma_f32 v[204:205], v[96:97], v[18:19], v[206:207]
	v_fmac_f32_e32 v139, v181, v1
	v_pk_fma_f32 v[30:31], v[94:95], v[18:19], v[30:31]
	v_fmac_f32_e32 v138, v180, v1
	v_pk_fma_f32 v[206:207], v[92:93], v[18:19], v[208:209]
	v_fmac_f32_e32 v137, v179, v1
	v_pk_fma_f32 v[28:29], v[90:91], v[18:19], v[28:29]
	v_fmac_f32_e32 v136, v178, v1
	v_pk_fma_f32 v[208:209], v[88:89], v[18:19], v[210:211]
	v_fmac_f32_e32 v135, v177, v1
	v_pk_fma_f32 v[26:27], v[86:87], v[18:19], v[26:27]
	v_fmac_f32_e32 v134, v176, v1
	v_pk_fma_f32 v[210:211], v[84:85], v[18:19], v[212:213]
	v_fmac_f32_e32 v133, v175, v1
	v_pk_fma_f32 v[24:25], v[82:83], v[18:19], v[24:25]
	v_fmac_f32_e32 v5, v174, v1
	v_pk_fma_f32 v[212:213], v[80:81], v[18:19], v[214:215]
	v_fmac_f32_e32 v2, v173, v1
	v_pk_fma_f32 v[16:17], v[78:79], v[18:19], v[16:17]
	v_fmac_f32_e32 v7, v172, v1
	v_lshlrev_b32_e32 v18, 16, v203
	v_and_b32_e32 v19, 0xffff0000, v203
	v_lshlrev_b32_e32 v1, 16, v202
	v_pk_fma_f32 v[20:21], v[110:111], v[18:19], v[20:21]
	v_fmac_f32_e32 v145, v188, v1
	v_pk_fma_f32 v[22:23], v[108:109], v[18:19], v[22:23]
	v_fmac_f32_e32 v144, v187, v1
	v_pk_fma_f32 v[36:37], v[106:107], v[18:19], v[36:37]
	v_fmac_f32_e32 v143, v186, v1
	v_pk_fma_f32 v[34:35], v[104:105], v[18:19], v[34:35]
	v_fmac_f32_e32 v142, v185, v1
	v_pk_fma_f32 v[38:39], v[102:103], v[18:19], v[38:39]
	v_fmac_f32_e32 v141, v184, v1
	v_pk_fma_f32 v[32:33], v[100:101], v[18:19], v[32:33]
	v_fmac_f32_e32 v140, v183, v1
	v_pk_fma_f32 v[202:203], v[98:99], v[18:19], v[204:205]
	v_fmac_f32_e32 v139, v182, v1
	v_pk_fma_f32 v[30:31], v[96:97], v[18:19], v[30:31]
	v_fmac_f32_e32 v138, v181, v1
	v_pk_fma_f32 v[204:205], v[94:95], v[18:19], v[206:207]
	v_fmac_f32_e32 v137, v180, v1
	v_pk_fma_f32 v[28:29], v[92:93], v[18:19], v[28:29]
	v_fmac_f32_e32 v136, v179, v1
	v_pk_fma_f32 v[206:207], v[90:91], v[18:19], v[208:209]
	v_fmac_f32_e32 v135, v178, v1
	v_pk_fma_f32 v[26:27], v[88:89], v[18:19], v[26:27]
	v_fmac_f32_e32 v134, v177, v1
	v_pk_fma_f32 v[208:209], v[86:87], v[18:19], v[210:211]
	v_fmac_f32_e32 v133, v176, v1
	v_pk_fma_f32 v[24:25], v[84:85], v[18:19], v[24:25]
; #define LAS __attribute__((address_space(3)))
; __device__ __forceinline__ float bf_lo(unsigned w) { return __uint_as_float(w << 16); }
; __device__ __forceinline__ float bf_hi(unsigned w) { return __uint_as_float(w & 0xffff0000u); }
; __device__ __forceinline__ void p2_conv_unit_prompt(Frame& F, int unit, int next_pm, const ConvW& cw, size_t src_off = WS_A, size_t dst_off = WS_CACT) {
;     ...
; #pragma unroll
;         for (int rg = 0; rg < CV_ROWS; rg += 8) {
;             unsigned w2[8], w1[8];
; #pragma unroll
;             for (int i = 0; i < 8; ++i) if (rg + i < CV_ROWS) { const LAS unsigned char* rp = S + (rg + i) * (DCONV * 2) + ((rg + i) < CW - 1 ? ringLo : ringHi);
;                 w2[i] = *(const LAS unsigned*)(rp + p * 2u); w1[i] = *(const LAS unsigned short*)(rp + q * 2u); }
; #pragma unroll
;             for (int i = 0; i < 8; ++i) if (rg + i < CV_ROWS) { const int rr = rg + i; const f32x2 vp = (f32x2){bf_lo(w2[i]), bf_hi(w2[i])}; const float vq = bf_lo(w1[i]);
; #pragma unroll
;                 for (int t = 0; t < 16; ++t) { const int j = rr - t; if (j >= 0 && j < CW) { ap[t] += wp[j] * vp; aq[t] += wq[j] * vq; } } }
;             __builtin_amdgcn_sched_barrier(0); }
	v_fmac_f32_e32 v5, v175, v1
	v_pk_fma_f32 v[210:211], v[82:83], v[18:19], v[212:213]
	v_fmac_f32_e32 v2, v174, v1
	v_pk_fma_f32 v[16:17], v[80:81], v[18:19], v[16:17]
	v_fmac_f32_e32 v7, v173, v1
	v_lshlrev_b32_e32 v18, 16, v41
	v_and_b32_e32 v19, 0xffff0000, v41
	v_lshlrev_b32_e32 v1, 16, v40
	v_pk_fma_f32 v[40:41], v[112:113], v[18:19], v[20:21]
	v_fmac_f32_e32 v145, v189, v1
	v_pk_fma_f32 v[20:21], v[110:111], v[18:19], v[22:23]
	v_fmac_f32_e32 v144, v188, v1
	v_pk_fma_f32 v[22:23], v[108:109], v[18:19], v[36:37]
	v_fmac_f32_e32 v143, v187, v1
	v_pk_fma_f32 v[34:35], v[106:107], v[18:19], v[34:35]
	v_fmac_f32_e32 v142, v186, v1
	v_pk_fma_f32 v[36:37], v[104:105], v[18:19], v[38:39]
	v_fmac_f32_e32 v141, v185, v1
	v_pk_fma_f32 v[32:33], v[102:103], v[18:19], v[32:33]
	v_fmac_f32_e32 v140, v184, v1
	v_pk_fma_f32 v[38:39], v[100:101], v[18:19], v[202:203]
	v_fmac_f32_e32 v139, v183, v1
	v_pk_fma_f32 v[30:31], v[98:99], v[18:19], v[30:31]
	v_fmac_f32_e32 v138, v182, v1
	v_pk_fma_f32 v[202:203], v[96:97], v[18:19], v[204:205]
	v_fmac_f32_e32 v137, v181, v1
	v_pk_fma_f32 v[28:29], v[94:95], v[18:19], v[28:29]
	v_fmac_f32_e32 v136, v180, v1
	v_pk_fma_f32 v[204:205], v[92:93], v[18:19], v[206:207]
	v_fmac_f32_e32 v135, v179, v1
	v_pk_fma_f32 v[26:27], v[90:91], v[18:19], v[26:27]
	v_fmac_f32_e32 v134, v178, v1
	v_pk_fma_f32 v[206:207], v[88:89], v[18:19], v[208:209]
	v_fmac_f32_e32 v133, v177, v1
	v_pk_fma_f32 v[24:25], v[86:87], v[18:19], v[24:25]
	v_fmac_f32_e32 v5, v176, v1
	v_pk_fma_f32 v[208:209], v[84:85], v[18:19], v[210:211]
	v_fmac_f32_e32 v2, v175, v1
	v_pk_fma_f32 v[16:17], v[82:83], v[18:19], v[16:17]
	v_fmac_f32_e32 v7, v174, v1
	v_lshlrev_b32_e32 v18, 16, v47
	v_and_b32_e32 v19, 0xffff0000, v47
	v_lshlrev_b32_e32 v1, 16, v46
	v_pk_fma_f32 v[46:47], v[112:113], v[18:19], v[20:21]
	v_fmac_f32_e32 v144, v189, v1
	v_pk_fma_f32 v[20:21], v[110:111], v[18:19], v[22:23]
	v_fmac_f32_e32 v143, v188, v1
	v_pk_fma_f32 v[22:23], v[108:109], v[18:19], v[34:35]
	v_fmac_f32_e32 v142, v187, v1
	v_pk_fma_f32 v[34:35], v[106:107], v[18:19], v[36:37]
	v_fmac_f32_e32 v141, v186, v1
	v_pk_fma_f32 v[32:33], v[104:105], v[18:19], v[32:33]
	v_fmac_f32_e32 v140, v185, v1
	v_pk_fma_f32 v[36:37], v[102:103], v[18:19], v[38:39]
	v_fmac_f32_e32 v139, v184, v1
	v_pk_fma_f32 v[30:31], v[100:101], v[18:19], v[30:31]
	v_fmac_f32_e32 v138, v183, v1
	v_pk_fma_f32 v[38:39], v[98:99], v[18:19], v[202:203]
	v_fmac_f32_e32 v137, v182, v1
	v_pk_fma_f32 v[28:29], v[96:97], v[18:19], v[28:29]
	v_fmac_f32_e32 v136, v181, v1
	v_pk_fma_f32 v[202:203], v[94:95], v[18:19], v[204:205]
	v_fmac_f32_e32 v135, v180, v1
	v_pk_fma_f32 v[26:27], v[92:93], v[18:19], v[26:27]
	v_fmac_f32_e32 v134, v179, v1
	v_pk_fma_f32 v[204:205], v[90:91], v[18:19], v[206:207]
	v_fmac_f32_e32 v133, v178, v1
	v_pk_fma_f32 v[24:25], v[88:89], v[18:19], v[24:25]
	v_fmac_f32_e32 v5, v177, v1
	v_pk_fma_f32 v[206:207], v[86:87], v[18:19], v[208:209]
	v_fmac_f32_e32 v2, v176, v1
	v_pk_fma_f32 v[16:17], v[84:85], v[18:19], v[16:17]
	v_fmac_f32_e32 v7, v175, v1
	v_lshlrev_b32_e32 v18, 16, v45
	v_and_b32_e32 v19, 0xffff0000, v45
	v_lshlrev_b32_e32 v1, 16, v44
	v_pk_fma_f32 v[44:45], v[112:113], v[18:19], v[20:21]
	v_fmac_f32_e32 v143, v189, v1
	v_pk_fma_f32 v[20:21], v[110:111], v[18:19], v[22:23]
	v_fmac_f32_e32 v142, v188, v1
	v_pk_fma_f32 v[22:23], v[108:109], v[18:19], v[34:35]
	v_fmac_f32_e32 v141, v187, v1
	v_pk_fma_f32 v[32:33], v[106:107], v[18:19], v[32:33]
	v_fmac_f32_e32 v140, v186, v1
	v_pk_fma_f32 v[34:35], v[104:105], v[18:19], v[36:37]
	v_fmac_f32_e32 v139, v185, v1
	v_pk_fma_f32 v[30:31], v[102:103], v[18:19], v[30:31]
	v_fmac_f32_e32 v138, v184, v1
	v_pk_fma_f32 v[36:37], v[100:101], v[18:19], v[38:39]
	v_fmac_f32_e32 v137, v183, v1
	v_pk_fma_f32 v[28:29], v[98:99], v[18:19], v[28:29]
	v_fmac_f32_e32 v136, v182, v1
	v_pk_fma_f32 v[38:39], v[96:97], v[18:19], v[202:203]
	v_fmac_f32_e32 v135, v181, v1
	v_pk_fma_f32 v[26:27], v[94:95], v[18:19], v[26:27]
	v_fmac_f32_e32 v134, v180, v1
	v_pk_fma_f32 v[202:203], v[92:93], v[18:19], v[204:205]
	v_fmac_f32_e32 v133, v179, v1
	v_pk_fma_f32 v[24:25], v[90:91], v[18:19], v[24:25]
	v_fmac_f32_e32 v5, v178, v1
	v_pk_fma_f32 v[204:205], v[88:89], v[18:19], v[206:207]
	v_fmac_f32_e32 v2, v177, v1
	v_pk_fma_f32 v[16:17], v[86:87], v[18:19], v[16:17]
	v_fmac_f32_e32 v7, v176, v1
	v_lshlrev_b32_e32 v18, 16, v43
	v_and_b32_e32 v19, 0xffff0000, v43
	v_lshlrev_b32_e32 v1, 16, v42
	v_pk_fma_f32 v[42:43], v[112:113], v[18:19], v[20:21]
	v_fmac_f32_e32 v142, v189, v1
	v_pk_fma_f32 v[20:21], v[110:111], v[18:19], v[22:23]
	v_fmac_f32_e32 v141, v188, v1
	v_pk_fma_f32 v[22:23], v[108:109], v[18:19], v[32:33]
	v_fmac_f32_e32 v140, v187, v1
	v_pk_fma_f32 v[32:33], v[106:107], v[18:19], v[34:35]
	v_fmac_f32_e32 v139, v186, v1
	v_pk_fma_f32 v[30:31], v[104:105], v[18:19], v[30:31]
	v_fmac_f32_e32 v138, v185, v1
	v_pk_fma_f32 v[34:35], v[102:103], v[18:19], v[36:37]
	v_fmac_f32_e32 v137, v184, v1
	v_pk_fma_f32 v[28:29], v[100:101], v[18:19], v[28:29]
	v_fmac_f32_e32 v136, v183, v1
	v_pk_fma_f32 v[36:37], v[98:99], v[18:19], v[38:39]
	v_fmac_f32_e32 v135, v182, v1
	v_pk_fma_f32 v[26:27], v[96:97], v[18:19], v[26:27]
	v_fmac_f32_e32 v134, v181, v1
	v_pk_fma_f32 v[202:203], v[94:95], v[18:19], v[202:203]
	v_fmac_f32_e32 v133, v180, v1
	v_pk_fma_f32 v[24:25], v[92:93], v[18:19], v[24:25]
	v_fmac_f32_e32 v5, v179, v1
	v_pk_fma_f32 v[204:205], v[90:91], v[18:19], v[204:205]
	v_fmac_f32_e32 v2, v178, v1
	v_pk_fma_f32 v[16:17], v[88:89], v[18:19], v[16:17]
	v_fmac_f32_e32 v7, v177, v1
	v_lshlrev_b32_e32 v18, 16, v201
	v_and_b32_e32 v19, 0xffff0000, v201
	v_lshlrev_b32_e32 v1, 16, v200
; #define LAS __attribute__((address_space(3)))
; __device__ __forceinline__ float bf_lo(unsigned w) { return __uint_as_float(w << 16); }
; __device__ __forceinline__ float bf_hi(unsigned w) { return __uint_as_float(w & 0xffff0000u); }
; __device__ __forceinline__ void p2_conv_unit_prompt(Frame& F, int unit, int next_pm, const ConvW& cw, size_t src_off = WS_A, size_t dst_off = WS_CACT) {
;     ...
; #pragma unroll
;         for (int rg = 0; rg < CV_ROWS; rg += 8) {
;             unsigned w2[8], w1[8];
; #pragma unroll
;             for (int i = 0; i < 8; ++i) if (rg + i < CV_ROWS) { const LAS unsigned char* rp = S + (rg + i) * (DCONV * 2) + ((rg + i) < CW - 1 ? ringLo : ringHi);
;                 w2[i] = *(const LAS unsigned*)(rp + p * 2u); w1[i] = *(const LAS unsigned short*)(rp + q * 2u); }
; #pragma unroll
;             for (int i = 0; i < 8; ++i) if (rg + i < CV_ROWS) { const int rr = rg + i; const f32x2 vp = (f32x2){bf_lo(w2[i]), bf_hi(w2[i])}; const float vq = bf_lo(w1[i]);
; #pragma unroll
;                 for (int t = 0; t < 16; ++t) { const int j = rr - t; if (j >= 0 && j < CW) { ap[t] += wp[j] * vp; aq[t] += wq[j] * vq; } } }
;             __builtin_amdgcn_sched_barrier(0); }
	v_pk_fma_f32 v[38:39], v[112:113], v[18:19], v[20:21]
	v_fmac_f32_e32 v141, v189, v1
	v_pk_fma_f32 v[20:21], v[110:111], v[18:19], v[22:23]
	v_fmac_f32_e32 v140, v188, v1
	v_pk_fma_f32 v[22:23], v[108:109], v[18:19], v[32:33]
	v_fmac_f32_e32 v139, v187, v1
	v_pk_fma_f32 v[30:31], v[106:107], v[18:19], v[30:31]
	v_fmac_f32_e32 v138, v186, v1
	v_pk_fma_f32 v[32:33], v[104:105], v[18:19], v[34:35]
	v_fmac_f32_e32 v137, v185, v1
	v_pk_fma_f32 v[28:29], v[102:103], v[18:19], v[28:29]
	v_fmac_f32_e32 v136, v184, v1
	v_pk_fma_f32 v[34:35], v[100:101], v[18:19], v[36:37]
	v_fmac_f32_e32 v135, v183, v1
	v_pk_fma_f32 v[26:27], v[98:99], v[18:19], v[26:27]
	v_fmac_f32_e32 v134, v182, v1
	v_pk_fma_f32 v[200:201], v[96:97], v[18:19], v[202:203]
	v_fmac_f32_e32 v133, v181, v1
	v_pk_fma_f32 v[24:25], v[94:95], v[18:19], v[24:25]
	v_fmac_f32_e32 v5, v180, v1
	v_pk_fma_f32 v[202:203], v[92:93], v[18:19], v[204:205]
	v_fmac_f32_e32 v2, v179, v1
	v_pk_fma_f32 v[16:17], v[90:91], v[18:19], v[16:17]
	v_fmac_f32_e32 v7, v178, v1
	v_lshlrev_b32_e32 v18, 16, v199
	v_and_b32_e32 v19, 0xffff0000, v199
	v_lshlrev_b32_e32 v1, 16, v198
	v_pk_fma_f32 v[36:37], v[112:113], v[18:19], v[20:21]
	v_fmac_f32_e32 v140, v189, v1
	v_pk_fma_f32 v[20:21], v[110:111], v[18:19], v[22:23]
	v_fmac_f32_e32 v139, v188, v1
	v_pk_fma_f32 v[22:23], v[108:109], v[18:19], v[30:31]
	v_fmac_f32_e32 v138, v187, v1
	v_pk_fma_f32 v[30:31], v[106:107], v[18:19], v[32:33]
	v_fmac_f32_e32 v137, v186, v1
	v_pk_fma_f32 v[28:29], v[104:105], v[18:19], v[28:29]
	v_fmac_f32_e32 v136, v185, v1
	v_pk_fma_f32 v[32:33], v[102:103], v[18:19], v[34:35]
	v_fmac_f32_e32 v135, v184, v1
	v_pk_fma_f32 v[26:27], v[100:101], v[18:19], v[26:27]
	v_fmac_f32_e32 v134, v183, v1
	v_pk_fma_f32 v[198:199], v[98:99], v[18:19], v[200:201]
	v_fmac_f32_e32 v133, v182, v1
	v_pk_fma_f32 v[24:25], v[96:97], v[18:19], v[24:25]
	v_fmac_f32_e32 v5, v181, v1
	v_pk_fma_f32 v[200:201], v[94:95], v[18:19], v[202:203]
	v_fmac_f32_e32 v2, v180, v1
	v_pk_fma_f32 v[16:17], v[92:93], v[18:19], v[16:17]
	v_fmac_f32_e32 v7, v179, v1
	v_lshlrev_b32_e32 v18, 16, v165
	v_and_b32_e32 v19, 0xffff0000, v165
	v_lshlrev_b32_e32 v1, 16, v164
	v_pk_fma_f32 v[34:35], v[112:113], v[18:19], v[20:21]
	v_fmac_f32_e32 v139, v189, v1
	v_pk_fma_f32 v[20:21], v[110:111], v[18:19], v[22:23]
	v_fmac_f32_e32 v138, v188, v1
	v_pk_fma_f32 v[22:23], v[108:109], v[18:19], v[30:31]
	v_fmac_f32_e32 v137, v187, v1
	v_pk_fma_f32 v[28:29], v[106:107], v[18:19], v[28:29]
	v_fmac_f32_e32 v136, v186, v1
	v_pk_fma_f32 v[30:31], v[104:105], v[18:19], v[32:33]
	v_fmac_f32_e32 v135, v185, v1
	v_pk_fma_f32 v[26:27], v[102:103], v[18:19], v[26:27]
	v_fmac_f32_e32 v134, v184, v1
	v_pk_fma_f32 v[164:165], v[100:101], v[18:19], v[198:199]
	v_fmac_f32_e32 v133, v183, v1
	v_pk_fma_f32 v[24:25], v[98:99], v[18:19], v[24:25]
	v_fmac_f32_e32 v5, v182, v1
	v_pk_fma_f32 v[198:199], v[96:97], v[18:19], v[200:201]
	v_fmac_f32_e32 v2, v181, v1
	v_pk_fma_f32 v[16:17], v[94:95], v[18:19], v[16:17]
	v_fmac_f32_e32 v7, v180, v1
	v_lshlrev_b32_e32 v18, 16, v163
	v_and_b32_e32 v19, 0xffff0000, v163
	v_lshlrev_b32_e32 v1, 16, v162
	v_pk_fma_f32 v[32:33], v[112:113], v[18:19], v[20:21]
	v_fmac_f32_e32 v138, v189, v1
	v_pk_fma_f32 v[20:21], v[110:111], v[18:19], v[22:23]
	v_fmac_f32_e32 v137, v188, v1
	v_pk_fma_f32 v[22:23], v[108:109], v[18:19], v[28:29]
	v_fmac_f32_e32 v136, v187, v1
	v_pk_fma_f32 v[28:29], v[106:107], v[18:19], v[30:31]
	v_fmac_f32_e32 v135, v186, v1
	v_pk_fma_f32 v[26:27], v[104:105], v[18:19], v[26:27]
	v_fmac_f32_e32 v134, v185, v1
	v_pk_fma_f32 v[162:163], v[102:103], v[18:19], v[164:165]
	v_fmac_f32_e32 v133, v184, v1
	v_pk_fma_f32 v[24:25], v[100:101], v[18:19], v[24:25]
	v_fmac_f32_e32 v5, v183, v1
	v_pk_fma_f32 v[164:165], v[98:99], v[18:19], v[198:199]
	v_fmac_f32_e32 v2, v182, v1
	v_pk_fma_f32 v[16:17], v[96:97], v[18:19], v[16:17]
	v_fmac_f32_e32 v7, v181, v1
	v_lshlrev_b32_e32 v18, 16, v161
	v_and_b32_e32 v19, 0xffff0000, v161
	v_lshlrev_b32_e32 v1, 16, v160
	v_pk_fma_f32 v[30:31], v[112:113], v[18:19], v[20:21]
	v_fmac_f32_e32 v137, v189, v1
	v_pk_fma_f32 v[20:21], v[110:111], v[18:19], v[22:23]
	v_fmac_f32_e32 v136, v188, v1
	v_pk_fma_f32 v[22:23], v[108:109], v[18:19], v[28:29]
	v_fmac_f32_e32 v135, v187, v1
	v_pk_fma_f32 v[26:27], v[106:107], v[18:19], v[26:27]
	v_fmac_f32_e32 v134, v186, v1
	v_pk_fma_f32 v[160:161], v[104:105], v[18:19], v[162:163]
	v_fmac_f32_e32 v133, v185, v1
	v_pk_fma_f32 v[24:25], v[102:103], v[18:19], v[24:25]
	v_fmac_f32_e32 v5, v184, v1
	v_pk_fma_f32 v[162:163], v[100:101], v[18:19], v[164:165]
	v_fmac_f32_e32 v2, v183, v1
	v_pk_fma_f32 v[16:17], v[98:99], v[18:19], v[16:17]
	v_fmac_f32_e32 v7, v182, v1
	v_lshlrev_b32_e32 v18, 16, v159
	v_and_b32_e32 v19, 0xffff0000, v159
	v_lshlrev_b32_e32 v1, 16, v158
	v_pk_fma_f32 v[28:29], v[112:113], v[18:19], v[20:21]
	v_fmac_f32_e32 v136, v189, v1
	v_pk_fma_f32 v[20:21], v[110:111], v[18:19], v[22:23]
	v_fmac_f32_e32 v135, v188, v1
	v_pk_fma_f32 v[22:23], v[108:109], v[18:19], v[26:27]
	v_fmac_f32_e32 v134, v187, v1
	v_pk_fma_f32 v[158:159], v[106:107], v[18:19], v[160:161]
	v_fmac_f32_e32 v133, v186, v1
	v_pk_fma_f32 v[24:25], v[104:105], v[18:19], v[24:25]
	v_fmac_f32_e32 v5, v185, v1
	v_pk_fma_f32 v[160:161], v[102:103], v[18:19], v[162:163]
	v_fmac_f32_e32 v2, v184, v1
	v_pk_fma_f32 v[16:17], v[100:101], v[18:19], v[16:17]
	v_fmac_f32_e32 v7, v183, v1
	v_lshlrev_b32_e32 v18, 16, v157
	v_and_b32_e32 v19, 0xffff0000, v157
	v_lshlrev_b32_e32 v1, 16, v156
	v_pk_fma_f32 v[26:27], v[112:113], v[18:19], v[20:21]
	v_fmac_f32_e32 v135, v189, v1
	v_pk_fma_f32 v[20:21], v[110:111], v[18:19], v[22:23]
; #define LDS_WAIT() asm volatile("s_waitcnt lgkmcnt(0)" ::: "memory")
; __device__ __forceinline__ float bf_lo(unsigned w) { return __uint_as_float(w << 16); }
; __device__ __forceinline__ float bf_hi(unsigned w) { return __uint_as_float(w & 0xffff0000u); }
; __device__ __forceinline__ void p2_conv_unit_prompt(Frame& F, int unit, int next_pm, const ConvW& cw, size_t src_off = WS_A, size_t dst_off = WS_CACT) {
;     ...
;             for (int i = 0; i < 8; ++i) if (rg + i < CV_ROWS) { const int rr = rg + i; const f32x2 vp = (f32x2){bf_lo(w2[i]), bf_hi(w2[i])}; const float vq = bf_lo(w1[i]);
; #pragma unroll
;                 for (int t = 0; t < 16; ++t) { const int j = rr - t; if (j >= 0 && j < CW) { ap[t] += wp[j] * vp; aq[t] += wq[j] * vq; } } }
;             __builtin_amdgcn_sched_barrier(0); }
;         LDS_WAIT(); __syncthreads();
;         if (h == 0) conv_stage_tail(F, S, rowA + 16, src_off);
;         else if (next_pm >= 0) poolmix_stage(F, next_pm);
;         float st[32];
; #pragma unroll
;         for (int t = 0; t < 16; ++t) { st[t] = (ap[t].x + ap[t].y) + aq[t]; st[16 + t] = (ap[t].x * ap[t].x + ap[t].y * ap[t].y) + aq[t] * aq[t]; }
;         float tot = 0.f;
; #pragma unroll
;         for (int i = 0; i < 32; ++i) { const float w = wave_sum(st[i]); asm volatile("v_writelane_b32 %0, %1, %2" : "+v"(tot) : "s"(w), "n"(i)); }
	v_fmac_f32_e32 v134, v188, v1
	v_pk_fma_f32 v[22:23], v[108:109], v[18:19], v[158:159]
	v_fmac_f32_e32 v133, v187, v1
	v_pk_fma_f32 v[156:157], v[106:107], v[18:19], v[24:25]
	v_fmac_f32_e32 v5, v186, v1
	v_pk_fma_f32 v[158:159], v[104:105], v[18:19], v[160:161]
	v_fmac_f32_e32 v2, v185, v1
	v_pk_fma_f32 v[16:17], v[102:103], v[18:19], v[16:17]
	v_fmac_f32_e32 v7, v184, v1
	v_lshlrev_b32_e32 v18, 16, v155
	v_and_b32_e32 v19, 0xffff0000, v155
	v_lshlrev_b32_e32 v1, 16, v154
	v_pk_fma_f32 v[24:25], v[112:113], v[18:19], v[20:21]
	v_fmac_f32_e32 v134, v189, v1
	v_pk_fma_f32 v[20:21], v[110:111], v[18:19], v[22:23]
	v_fmac_f32_e32 v133, v188, v1
	v_pk_fma_f32 v[154:155], v[108:109], v[18:19], v[156:157]
	v_fmac_f32_e32 v5, v187, v1
	v_pk_fma_f32 v[156:157], v[106:107], v[18:19], v[158:159]
	v_fmac_f32_e32 v2, v186, v1
	v_pk_fma_f32 v[16:17], v[104:105], v[18:19], v[16:17]
	v_fmac_f32_e32 v7, v185, v1
	v_lshlrev_b32_e32 v18, 16, v153
	v_and_b32_e32 v19, 0xffff0000, v153
	v_lshlrev_b32_e32 v1, 16, v152
	v_pk_fma_f32 v[22:23], v[112:113], v[18:19], v[20:21]
	v_fmac_f32_e32 v133, v189, v1
	v_pk_fma_f32 v[20:21], v[110:111], v[18:19], v[154:155]
	v_fmac_f32_e32 v5, v188, v1
	v_pk_fma_f32 v[152:153], v[108:109], v[18:19], v[156:157]
	v_fmac_f32_e32 v2, v187, v1
	v_pk_fma_f32 v[16:17], v[106:107], v[18:19], v[16:17]
	v_fmac_f32_e32 v7, v186, v1
	v_lshlrev_b32_e32 v18, 16, v151
	v_and_b32_e32 v19, 0xffff0000, v151
	v_lshlrev_b32_e32 v1, 16, v150
	v_fmac_f32_e32 v5, v189, v1
	v_pk_fma_f32 v[150:151], v[110:111], v[18:19], v[152:153]
	v_fmac_f32_e32 v2, v188, v1
	v_pk_fma_f32 v[16:17], v[108:109], v[18:19], v[16:17]
	v_fmac_f32_e32 v7, v187, v1
	v_lshlrev_b32_e32 v152, 16, v149
	v_and_b32_e32 v153, 0xffff0000, v149
	v_lshlrev_b32_e32 v1, 16, v148
	v_fmac_f32_e32 v2, v189, v1
	v_pk_fma_f32 v[16:17], v[110:111], v[152:153], v[16:17]
	v_fmac_f32_e32 v7, v188, v1
	v_lshlrev_b32_e32 v148, 16, v147
	v_and_b32_e32 v149, 0xffff0000, v147
	v_lshlrev_b32_e32 v1, 16, v146
	v_pk_mul_f32 v[146:147], v[40:41], v[40:41]
	v_pk_fma_f32 v[16:17], v[112:113], v[148:149], v[16:17]
	v_add_f32_e32 v148, v146, v147
	v_add_f32_e32 v146, v46, v47
	v_add_f32_e32 v149, v144, v146
	v_pk_mul_f32 v[146:147], v[46:47], v[46:47]
	v_pk_fma_f32 v[20:21], v[112:113], v[18:19], v[20:21]
	v_pk_fma_f32 v[18:19], v[112:113], v[152:153], v[150:151]
	v_add_f32_e32 v150, v146, v147
	v_add_f32_e32 v146, v44, v45
	v_add_f32_e32 v151, v143, v146
	v_pk_mul_f32 v[146:147], v[44:45], v[44:45]
	v_fmac_f32_e32 v7, v189, v1
	v_add_f32_e32 v152, v146, v147
	v_add_f32_e32 v146, v42, v43
	v_add_f32_e32 v153, v142, v146
	v_pk_mul_f32 v[146:147], v[42:43], v[42:43]
	v_add_f32_e32 v1, v40, v41
	v_add_f32_e32 v154, v146, v147
	v_add_f32_e32 v146, v38, v39
	v_add_f32_e32 v155, v141, v146
	v_pk_mul_f32 v[146:147], v[38:39], v[38:39]
	v_add_f32_e32 v1, v145, v1
	v_add_f32_e32 v156, v146, v147
	v_add_f32_e32 v146, v36, v37
	v_add_f32_e32 v157, v140, v146
	v_pk_mul_f32 v[146:147], v[36:37], v[36:37]
	v_add_f32_dpp v1, v1, v1 quad_perm:[1,0,3,2] row_mask:0xf bank_mask:0xf bound_ctrl:1
	v_add_f32_e32 v158, v146, v147
	v_add_f32_e32 v146, v34, v35
	v_add_f32_e32 v159, v139, v146
	v_pk_mul_f32 v[146:147], v[34:35], v[34:35]
	v_add_f32_dpp v1, v1, v1 quad_perm:[2,3,0,1] row_mask:0xf bank_mask:0xf bound_ctrl:1
	v_add_f32_e32 v160, v146, v147
	v_add_f32_e32 v146, v32, v33
	v_add_f32_e32 v161, v138, v146
	v_pk_mul_f32 v[146:147], v[32:33], v[32:33]
	v_add_f32_dpp v1, v1, v1 row_half_mirror row_mask:0xf bank_mask:0xf bound_ctrl:1
	v_add_f32_e32 v162, v146, v147
	v_add_f32_e32 v146, v30, v31
	v_add_f32_e32 v163, v137, v146
	v_pk_mul_f32 v[146:147], v[30:31], v[30:31]
	v_add_f32_dpp v1, v1, v1 row_mirror row_mask:0xf bank_mask:0xf bound_ctrl:1
	v_add_f32_e32 v164, v146, v147
	v_add_f32_e32 v146, v28, v29
	v_add_f32_e32 v165, v136, v146
	v_pk_mul_f32 v[146:147], v[28:29], v[28:29]
	v_fmac_f32_e32 v148, v145, v145
	v_add_f32_e32 v198, v146, v147
	v_add_f32_e32 v146, v26, v27
	v_add_f32_e32 v199, v135, v146
	v_pk_mul_f32 v[146:147], v[26:27], v[26:27]
	v_fmac_f32_e32 v150, v144, v144
	v_add_f32_e32 v200, v146, v147
	v_add_f32_e32 v146, v24, v25
	v_add_f32_e32 v201, v134, v146
	v_pk_mul_f32 v[146:147], v[24:25], v[24:25]
	v_fmac_f32_e32 v152, v143, v143
	v_add_f32_e32 v202, v146, v147
	v_add_f32_e32 v146, v22, v23
	v_add_f32_e32 v203, v133, v146
	v_pk_mul_f32 v[146:147], v[22:23], v[22:23]
	v_fmac_f32_e32 v154, v142, v142
	v_add_f32_e32 v204, v146, v147
	v_add_f32_e32 v146, v20, v21
	v_add_f32_e32 v205, v5, v146
	v_pk_mul_f32 v[146:147], v[20:21], v[20:21]
	v_fmac_f32_e32 v156, v141, v141
	v_add_f32_e32 v206, v146, v147
	v_add_f32_e32 v146, v18, v19
	v_add_f32_e32 v207, v2, v146
	v_pk_mul_f32 v[146:147], v[18:19], v[18:19]
	v_fmac_f32_e32 v158, v140, v140
	v_add_f32_e32 v208, v146, v147
	v_add_f32_e32 v146, v16, v17
	v_add_f32_e32 v209, v7, v146
	v_pk_mul_f32 v[146:147], v[16:17], v[16:17]
	v_fmac_f32_e32 v160, v139, v139
	v_add_f32_e32 v147, v146, v147
	v_mov_b32_e32 v146, v3
	v_fmac_f32_e32 v162, v138, v138
	v_fmac_f32_e32 v164, v137, v137
	v_mov_b32_dpp v146, v1 row_bcast:15 row_mask:0xa bank_mask:0xf
	v_add_f32_e32 v1, v1, v146
	v_mov_b32_e32 v146, v3
	v_fmac_f32_e32 v198, v136, v136
	v_fmac_f32_e32 v200, v135, v135
	v_mov_b32_dpp v146, v1 row_bcast:31 row_mask:0xc bank_mask:0xf
	v_add_f32_e32 v1, v1, v146
	v_mov_b32_e32 v146, v3
	v_readlane_b32 s12, v1, 63
	v_fmac_f32_e32 v202, v134, v134
	v_fmac_f32_e32 v204, v133, v133
	v_fmac_f32_e32 v206, v5, v5
	v_fmac_f32_e32 v208, v2, v2
	v_fmac_f32_e32 v147, v7, v7
	v_writelane_b32 v146, s12, 0
	v_add_f32_dpp v149, v149, v149 quad_perm:[1,0,3,2] row_mask:0xf bank_mask:0xf bound_ctrl:1
; template <int CTRL, int RM> __device__ __forceinline__ float dppf(float v) { return __builtin_bit_cast(float, __builtin_amdgcn_update_dpp(0, __builtin_bit_cast(int, v), CTRL, RM, 0xF, false)); }
; __device__ __forceinline__ float row_sum_dpp(float v) {
;     v += dppf<0xB1, 0xF>(v); v += dppf<0x4E, 0xF>(v); v += dppf<0x141, 0xF>(v); v += dppf<0x140, 0xF>(v); return v; }
; __device__ __forceinline__ float half_sum_dpp(float v) {
;     v = row_sum_dpp(v); v += dppf<0x142, 0xA>(v); return v; }
; __device__ __forceinline__ float wave_sum(float v) {
;     v = half_sum_dpp(v); v += dppf<0x143, 0xC>(v);
;     return __builtin_bit_cast(float, __builtin_amdgcn_readlane(__builtin_bit_cast(int, v), 63)); }
; __device__ __forceinline__ void p2_conv_unit_prompt(Frame& F, int unit, int next_pm, const ConvW& cw, size_t src_off = WS_A, size_t dst_off = WS_CACT) {
;     ...
;         for (int i = 0; i < 32; ++i) { const float w = wave_sum(st[i]); asm volatile("v_writelane_b32 %0, %1, %2" : "+v"(tot) : "s"(w), "n"(i)); }
	v_add_f32_dpp v151, v151, v151 quad_perm:[1,0,3,2] row_mask:0xf bank_mask:0xf bound_ctrl:1
	v_add_f32_dpp v153, v153, v153 quad_perm:[1,0,3,2] row_mask:0xf bank_mask:0xf bound_ctrl:1
	v_add_f32_dpp v155, v155, v155 quad_perm:[1,0,3,2] row_mask:0xf bank_mask:0xf bound_ctrl:1
	v_add_f32_dpp v157, v157, v157 quad_perm:[1,0,3,2] row_mask:0xf bank_mask:0xf bound_ctrl:1
	v_add_f32_dpp v159, v159, v159 quad_perm:[1,0,3,2] row_mask:0xf bank_mask:0xf bound_ctrl:1
	v_add_f32_dpp v161, v161, v161 quad_perm:[1,0,3,2] row_mask:0xf bank_mask:0xf bound_ctrl:1
	v_add_f32_dpp v163, v163, v163 quad_perm:[1,0,3,2] row_mask:0xf bank_mask:0xf bound_ctrl:1
	v_add_f32_dpp v165, v165, v165 quad_perm:[1,0,3,2] row_mask:0xf bank_mask:0xf bound_ctrl:1
	v_add_f32_dpp v199, v199, v199 quad_perm:[1,0,3,2] row_mask:0xf bank_mask:0xf bound_ctrl:1
	v_add_f32_dpp v201, v201, v201 quad_perm:[1,0,3,2] row_mask:0xf bank_mask:0xf bound_ctrl:1
	v_add_f32_dpp v203, v203, v203 quad_perm:[1,0,3,2] row_mask:0xf bank_mask:0xf bound_ctrl:1
	v_add_f32_dpp v205, v205, v205 quad_perm:[1,0,3,2] row_mask:0xf bank_mask:0xf bound_ctrl:1
	v_add_f32_dpp v207, v207, v207 quad_perm:[1,0,3,2] row_mask:0xf bank_mask:0xf bound_ctrl:1
	v_add_f32_dpp v209, v209, v209 quad_perm:[1,0,3,2] row_mask:0xf bank_mask:0xf bound_ctrl:1
	v_add_f32_dpp v148, v148, v148 quad_perm:[1,0,3,2] row_mask:0xf bank_mask:0xf bound_ctrl:1
	v_add_f32_dpp v150, v150, v150 quad_perm:[1,0,3,2] row_mask:0xf bank_mask:0xf bound_ctrl:1
	v_add_f32_dpp v152, v152, v152 quad_perm:[1,0,3,2] row_mask:0xf bank_mask:0xf bound_ctrl:1
	v_add_f32_dpp v154, v154, v154 quad_perm:[1,0,3,2] row_mask:0xf bank_mask:0xf bound_ctrl:1
	v_add_f32_dpp v156, v156, v156 quad_perm:[1,0,3,2] row_mask:0xf bank_mask:0xf bound_ctrl:1
	v_add_f32_dpp v158, v158, v158 quad_perm:[1,0,3,2] row_mask:0xf bank_mask:0xf bound_ctrl:1
	v_add_f32_dpp v160, v160, v160 quad_perm:[1,0,3,2] row_mask:0xf bank_mask:0xf bound_ctrl:1
	v_add_f32_dpp v162, v162, v162 quad_perm:[1,0,3,2] row_mask:0xf bank_mask:0xf bound_ctrl:1
	v_add_f32_dpp v164, v164, v164 quad_perm:[1,0,3,2] row_mask:0xf bank_mask:0xf bound_ctrl:1
	v_add_f32_dpp v198, v198, v198 quad_perm:[1,0,3,2] row_mask:0xf bank_mask:0xf bound_ctrl:1
	v_add_f32_dpp v200, v200, v200 quad_perm:[1,0,3,2] row_mask:0xf bank_mask:0xf bound_ctrl:1
	v_add_f32_dpp v202, v202, v202 quad_perm:[1,0,3,2] row_mask:0xf bank_mask:0xf bound_ctrl:1
	v_add_f32_dpp v204, v204, v204 quad_perm:[1,0,3,2] row_mask:0xf bank_mask:0xf bound_ctrl:1
	v_add_f32_dpp v206, v206, v206 quad_perm:[1,0,3,2] row_mask:0xf bank_mask:0xf bound_ctrl:1
	v_add_f32_dpp v208, v208, v208 quad_perm:[1,0,3,2] row_mask:0xf bank_mask:0xf bound_ctrl:1
	v_add_f32_dpp v147, v147, v147 quad_perm:[1,0,3,2] row_mask:0xf bank_mask:0xf bound_ctrl:1
	v_add_f32_dpp v149, v149, v149 quad_perm:[2,3,0,1] row_mask:0xf bank_mask:0xf bound_ctrl:1
	v_add_f32_dpp v151, v151, v151 quad_perm:[2,3,0,1] row_mask:0xf bank_mask:0xf bound_ctrl:1
	v_add_f32_dpp v153, v153, v153 quad_perm:[2,3,0,1] row_mask:0xf bank_mask:0xf bound_ctrl:1
	v_add_f32_dpp v155, v155, v155 quad_perm:[2,3,0,1] row_mask:0xf bank_mask:0xf bound_ctrl:1
	v_add_f32_dpp v157, v157, v157 quad_perm:[2,3,0,1] row_mask:0xf bank_mask:0xf bound_ctrl:1
	v_add_f32_dpp v159, v159, v159 quad_perm:[2,3,0,1] row_mask:0xf bank_mask:0xf bound_ctrl:1
	v_add_f32_dpp v161, v161, v161 quad_perm:[2,3,0,1] row_mask:0xf bank_mask:0xf bound_ctrl:1
	v_add_f32_dpp v163, v163, v163 quad_perm:[2,3,0,1] row_mask:0xf bank_mask:0xf bound_ctrl:1
	v_add_f32_dpp v165, v165, v165 quad_perm:[2,3,0,1] row_mask:0xf bank_mask:0xf bound_ctrl:1
	v_add_f32_dpp v199, v199, v199 quad_perm:[2,3,0,1] row_mask:0xf bank_mask:0xf bound_ctrl:1
	v_add_f32_dpp v201, v201, v201 quad_perm:[2,3,0,1] row_mask:0xf bank_mask:0xf bound_ctrl:1
	v_add_f32_dpp v203, v203, v203 quad_perm:[2,3,0,1] row_mask:0xf bank_mask:0xf bound_ctrl:1
	v_add_f32_dpp v205, v205, v205 quad_perm:[2,3,0,1] row_mask:0xf bank_mask:0xf bound_ctrl:1
	v_add_f32_dpp v207, v207, v207 quad_perm:[2,3,0,1] row_mask:0xf bank_mask:0xf bound_ctrl:1
	v_add_f32_dpp v209, v209, v209 quad_perm:[2,3,0,1] row_mask:0xf bank_mask:0xf bound_ctrl:1
	v_add_f32_dpp v148, v148, v148 quad_perm:[2,3,0,1] row_mask:0xf bank_mask:0xf bound_ctrl:1
	v_add_f32_dpp v150, v150, v150 quad_perm:[2,3,0,1] row_mask:0xf bank_mask:0xf bound_ctrl:1
	v_add_f32_dpp v152, v152, v152 quad_perm:[2,3,0,1] row_mask:0xf bank_mask:0xf bound_ctrl:1
	v_add_f32_dpp v154, v154, v154 quad_perm:[2,3,0,1] row_mask:0xf bank_mask:0xf bound_ctrl:1
	v_add_f32_dpp v156, v156, v156 quad_perm:[2,3,0,1] row_mask:0xf bank_mask:0xf bound_ctrl:1
	v_add_f32_dpp v158, v158, v158 quad_perm:[2,3,0,1] row_mask:0xf bank_mask:0xf bound_ctrl:1
	v_add_f32_dpp v160, v160, v160 quad_perm:[2,3,0,1] row_mask:0xf bank_mask:0xf bound_ctrl:1
	v_add_f32_dpp v162, v162, v162 quad_perm:[2,3,0,1] row_mask:0xf bank_mask:0xf bound_ctrl:1
	v_add_f32_dpp v164, v164, v164 quad_perm:[2,3,0,1] row_mask:0xf bank_mask:0xf bound_ctrl:1
	v_add_f32_dpp v198, v198, v198 quad_perm:[2,3,0,1] row_mask:0xf bank_mask:0xf bound_ctrl:1
	v_add_f32_dpp v200, v200, v200 quad_perm:[2,3,0,1] row_mask:0xf bank_mask:0xf bound_ctrl:1
	v_add_f32_dpp v202, v202, v202 quad_perm:[2,3,0,1] row_mask:0xf bank_mask:0xf bound_ctrl:1
	v_add_f32_dpp v204, v204, v204 quad_perm:[2,3,0,1] row_mask:0xf bank_mask:0xf bound_ctrl:1
	v_add_f32_dpp v206, v206, v206 quad_perm:[2,3,0,1] row_mask:0xf bank_mask:0xf bound_ctrl:1
	v_add_f32_dpp v208, v208, v208 quad_perm:[2,3,0,1] row_mask:0xf bank_mask:0xf bound_ctrl:1
	v_add_f32_dpp v147, v147, v147 quad_perm:[2,3,0,1] row_mask:0xf bank_mask:0xf bound_ctrl:1
; template <int CTRL, int RM> __device__ __forceinline__ float dppf(float v) { return __builtin_bit_cast(float, __builtin_amdgcn_update_dpp(0, __builtin_bit_cast(int, v), CTRL, RM, 0xF, false)); }
; __device__ __forceinline__ float row_sum_dpp(float v) {
;     v += dppf<0xB1, 0xF>(v); v += dppf<0x4E, 0xF>(v); v += dppf<0x141, 0xF>(v); v += dppf<0x140, 0xF>(v); return v; }
; __device__ __forceinline__ float half_sum_dpp(float v) {
;     v = row_sum_dpp(v); v += dppf<0x142, 0xA>(v); return v; }
; __device__ __forceinline__ float wave_sum(float v) {
;     v = half_sum_dpp(v); v += dppf<0x143, 0xC>(v);
;     return __builtin_bit_cast(float, __builtin_amdgcn_readlane(__builtin_bit_cast(int, v), 63)); }
; __device__ __forceinline__ void p2_conv_unit_prompt(Frame& F, int unit, int next_pm, const ConvW& cw, size_t src_off = WS_A, size_t dst_off = WS_CACT) {
;     ...
;         for (int i = 0; i < 32; ++i) { const float w = wave_sum(st[i]); asm volatile("v_writelane_b32 %0, %1, %2" : "+v"(tot) : "s"(w), "n"(i)); }
	v_add_f32_dpp v149, v149, v149 row_half_mirror row_mask:0xf bank_mask:0xf bound_ctrl:1
	v_add_f32_dpp v151, v151, v151 row_half_mirror row_mask:0xf bank_mask:0xf bound_ctrl:1
	v_add_f32_dpp v153, v153, v153 row_half_mirror row_mask:0xf bank_mask:0xf bound_ctrl:1
	v_add_f32_dpp v155, v155, v155 row_half_mirror row_mask:0xf bank_mask:0xf bound_ctrl:1
	v_add_f32_dpp v157, v157, v157 row_half_mirror row_mask:0xf bank_mask:0xf bound_ctrl:1
	v_add_f32_dpp v159, v159, v159 row_half_mirror row_mask:0xf bank_mask:0xf bound_ctrl:1
	v_add_f32_dpp v161, v161, v161 row_half_mirror row_mask:0xf bank_mask:0xf bound_ctrl:1
	v_add_f32_dpp v163, v163, v163 row_half_mirror row_mask:0xf bank_mask:0xf bound_ctrl:1
	v_add_f32_dpp v165, v165, v165 row_half_mirror row_mask:0xf bank_mask:0xf bound_ctrl:1
	v_add_f32_dpp v199, v199, v199 row_half_mirror row_mask:0xf bank_mask:0xf bound_ctrl:1
	v_add_f32_dpp v201, v201, v201 row_half_mirror row_mask:0xf bank_mask:0xf bound_ctrl:1
	v_add_f32_dpp v203, v203, v203 row_half_mirror row_mask:0xf bank_mask:0xf bound_ctrl:1
	v_add_f32_dpp v205, v205, v205 row_half_mirror row_mask:0xf bank_mask:0xf bound_ctrl:1
	v_add_f32_dpp v207, v207, v207 row_half_mirror row_mask:0xf bank_mask:0xf bound_ctrl:1
	v_add_f32_dpp v209, v209, v209 row_half_mirror row_mask:0xf bank_mask:0xf bound_ctrl:1
	v_add_f32_dpp v148, v148, v148 row_half_mirror row_mask:0xf bank_mask:0xf bound_ctrl:1
	v_add_f32_dpp v150, v150, v150 row_half_mirror row_mask:0xf bank_mask:0xf bound_ctrl:1
	v_add_f32_dpp v152, v152, v152 row_half_mirror row_mask:0xf bank_mask:0xf bound_ctrl:1
	v_add_f32_dpp v154, v154, v154 row_half_mirror row_mask:0xf bank_mask:0xf bound_ctrl:1
	v_add_f32_dpp v156, v156, v156 row_half_mirror row_mask:0xf bank_mask:0xf bound_ctrl:1
	v_add_f32_dpp v158, v158, v158 row_half_mirror row_mask:0xf bank_mask:0xf bound_ctrl:1
	v_add_f32_dpp v160, v160, v160 row_half_mirror row_mask:0xf bank_mask:0xf bound_ctrl:1
	v_add_f32_dpp v162, v162, v162 row_half_mirror row_mask:0xf bank_mask:0xf bound_ctrl:1
	v_add_f32_dpp v164, v164, v164 row_half_mirror row_mask:0xf bank_mask:0xf bound_ctrl:1
	v_add_f32_dpp v198, v198, v198 row_half_mirror row_mask:0xf bank_mask:0xf bound_ctrl:1
	v_add_f32_dpp v200, v200, v200 row_half_mirror row_mask:0xf bank_mask:0xf bound_ctrl:1
	v_add_f32_dpp v202, v202, v202 row_half_mirror row_mask:0xf bank_mask:0xf bound_ctrl:1
	v_add_f32_dpp v204, v204, v204 row_half_mirror row_mask:0xf bank_mask:0xf bound_ctrl:1
	v_add_f32_dpp v206, v206, v206 row_half_mirror row_mask:0xf bank_mask:0xf bound_ctrl:1
	v_add_f32_dpp v208, v208, v208 row_half_mirror row_mask:0xf bank_mask:0xf bound_ctrl:1
	v_add_f32_dpp v147, v147, v147 row_half_mirror row_mask:0xf bank_mask:0xf bound_ctrl:1
	v_add_f32_dpp v149, v149, v149 row_mirror row_mask:0xf bank_mask:0xf bound_ctrl:1
	v_add_f32_dpp v151, v151, v151 row_mirror row_mask:0xf bank_mask:0xf bound_ctrl:1
	v_add_f32_dpp v153, v153, v153 row_mirror row_mask:0xf bank_mask:0xf bound_ctrl:1
	v_add_f32_dpp v155, v155, v155 row_mirror row_mask:0xf bank_mask:0xf bound_ctrl:1
	v_add_f32_dpp v157, v157, v157 row_mirror row_mask:0xf bank_mask:0xf bound_ctrl:1
	v_add_f32_dpp v159, v159, v159 row_mirror row_mask:0xf bank_mask:0xf bound_ctrl:1
	v_add_f32_dpp v161, v161, v161 row_mirror row_mask:0xf bank_mask:0xf bound_ctrl:1
	v_add_f32_dpp v163, v163, v163 row_mirror row_mask:0xf bank_mask:0xf bound_ctrl:1
	v_add_f32_dpp v165, v165, v165 row_mirror row_mask:0xf bank_mask:0xf bound_ctrl:1
	v_add_f32_dpp v199, v199, v199 row_mirror row_mask:0xf bank_mask:0xf bound_ctrl:1
	v_add_f32_dpp v201, v201, v201 row_mirror row_mask:0xf bank_mask:0xf bound_ctrl:1
	v_add_f32_dpp v203, v203, v203 row_mirror row_mask:0xf bank_mask:0xf bound_ctrl:1
	v_add_f32_dpp v205, v205, v205 row_mirror row_mask:0xf bank_mask:0xf bound_ctrl:1
	v_add_f32_dpp v207, v207, v207 row_mirror row_mask:0xf bank_mask:0xf bound_ctrl:1
	v_add_f32_dpp v209, v209, v209 row_mirror row_mask:0xf bank_mask:0xf bound_ctrl:1
	v_add_f32_dpp v148, v148, v148 row_mirror row_mask:0xf bank_mask:0xf bound_ctrl:1
	v_add_f32_dpp v150, v150, v150 row_mirror row_mask:0xf bank_mask:0xf bound_ctrl:1
	v_add_f32_dpp v152, v152, v152 row_mirror row_mask:0xf bank_mask:0xf bound_ctrl:1
	v_add_f32_dpp v154, v154, v154 row_mirror row_mask:0xf bank_mask:0xf bound_ctrl:1
	v_add_f32_dpp v156, v156, v156 row_mirror row_mask:0xf bank_mask:0xf bound_ctrl:1
	v_add_f32_dpp v158, v158, v158 row_mirror row_mask:0xf bank_mask:0xf bound_ctrl:1
	v_add_f32_dpp v160, v160, v160 row_mirror row_mask:0xf bank_mask:0xf bound_ctrl:1
	v_add_f32_dpp v162, v162, v162 row_mirror row_mask:0xf bank_mask:0xf bound_ctrl:1
	v_add_f32_dpp v164, v164, v164 row_mirror row_mask:0xf bank_mask:0xf bound_ctrl:1
	v_add_f32_dpp v198, v198, v198 row_mirror row_mask:0xf bank_mask:0xf bound_ctrl:1
	v_add_f32_dpp v200, v200, v200 row_mirror row_mask:0xf bank_mask:0xf bound_ctrl:1
	v_add_f32_dpp v202, v202, v202 row_mirror row_mask:0xf bank_mask:0xf bound_ctrl:1
	v_add_f32_dpp v204, v204, v204 row_mirror row_mask:0xf bank_mask:0xf bound_ctrl:1
	v_add_f32_dpp v206, v206, v206 row_mirror row_mask:0xf bank_mask:0xf bound_ctrl:1
	v_add_f32_dpp v208, v208, v208 row_mirror row_mask:0xf bank_mask:0xf bound_ctrl:1
	v_add_f32_dpp v147, v147, v147 row_mirror row_mask:0xf bank_mask:0xf bound_ctrl:1
	v_add_f32_dpp v149, v149, v149 row_bcast:15 row_mask:0xa bank_mask:0xf
	v_add_f32_dpp v151, v151, v151 row_bcast:15 row_mask:0xa bank_mask:0xf
	v_add_f32_dpp v153, v153, v153 row_bcast:15 row_mask:0xa bank_mask:0xf
	v_add_f32_dpp v155, v155, v155 row_bcast:15 row_mask:0xa bank_mask:0xf
	v_add_f32_dpp v157, v157, v157 row_bcast:15 row_mask:0xa bank_mask:0xf
; #define LDS_WAIT() asm volatile("s_waitcnt lgkmcnt(0)" ::: "memory")
; template <int CTRL, int RM> __device__ __forceinline__ float dppf(float v) { return __builtin_bit_cast(float, __builtin_amdgcn_update_dpp(0, __builtin_bit_cast(int, v), CTRL, RM, 0xF, false)); }
; __device__ __forceinline__ float row_sum_dpp(float v) {
;     v += dppf<0xB1, 0xF>(v); v += dppf<0x4E, 0xF>(v); v += dppf<0x141, 0xF>(v); v += dppf<0x140, 0xF>(v); return v; }
; __device__ __forceinline__ float half_sum_dpp(float v) {
;     v = row_sum_dpp(v); v += dppf<0x142, 0xA>(v); return v; }
; __device__ __forceinline__ float wave_sum(float v) {
;     v = half_sum_dpp(v); v += dppf<0x143, 0xC>(v);
;     return __builtin_bit_cast(float, __builtin_amdgcn_readlane(__builtin_bit_cast(int, v), 63)); }
; __device__ __forceinline__ void p2_conv_unit_prompt(Frame& F, int unit, int next_pm, const ConvW& cw, size_t src_off = WS_A, size_t dst_off = WS_CACT) {
;     ...
;         for (int i = 0; i < 32; ++i) { const float w = wave_sum(st[i]); asm volatile("v_writelane_b32 %0, %1, %2" : "+v"(tot) : "s"(w), "n"(i)); }
;         if (ln < 32u) WPT[F.wave * 32 + (int)ln] = tot;
;         LDS_WAIT(); __syncthreads();
	v_add_f32_dpp v159, v159, v159 row_bcast:15 row_mask:0xa bank_mask:0xf
	v_add_f32_dpp v161, v161, v161 row_bcast:15 row_mask:0xa bank_mask:0xf
	v_add_f32_dpp v163, v163, v163 row_bcast:15 row_mask:0xa bank_mask:0xf
	v_add_f32_dpp v165, v165, v165 row_bcast:15 row_mask:0xa bank_mask:0xf
	v_add_f32_dpp v199, v199, v199 row_bcast:15 row_mask:0xa bank_mask:0xf
	v_add_f32_dpp v201, v201, v201 row_bcast:15 row_mask:0xa bank_mask:0xf
	v_add_f32_dpp v203, v203, v203 row_bcast:15 row_mask:0xa bank_mask:0xf
	v_add_f32_dpp v205, v205, v205 row_bcast:15 row_mask:0xa bank_mask:0xf
	v_add_f32_dpp v207, v207, v207 row_bcast:15 row_mask:0xa bank_mask:0xf
	v_add_f32_dpp v209, v209, v209 row_bcast:15 row_mask:0xa bank_mask:0xf
	v_add_f32_dpp v148, v148, v148 row_bcast:15 row_mask:0xa bank_mask:0xf
	v_add_f32_dpp v150, v150, v150 row_bcast:15 row_mask:0xa bank_mask:0xf
	v_add_f32_dpp v152, v152, v152 row_bcast:15 row_mask:0xa bank_mask:0xf
	v_add_f32_dpp v154, v154, v154 row_bcast:15 row_mask:0xa bank_mask:0xf
	v_add_f32_dpp v156, v156, v156 row_bcast:15 row_mask:0xa bank_mask:0xf
	v_add_f32_dpp v158, v158, v158 row_bcast:15 row_mask:0xa bank_mask:0xf
	v_add_f32_dpp v160, v160, v160 row_bcast:15 row_mask:0xa bank_mask:0xf
	v_add_f32_dpp v162, v162, v162 row_bcast:15 row_mask:0xa bank_mask:0xf
	v_add_f32_dpp v164, v164, v164 row_bcast:15 row_mask:0xa bank_mask:0xf
	v_add_f32_dpp v198, v198, v198 row_bcast:15 row_mask:0xa bank_mask:0xf
	v_add_f32_dpp v200, v200, v200 row_bcast:15 row_mask:0xa bank_mask:0xf
	v_add_f32_dpp v202, v202, v202 row_bcast:15 row_mask:0xa bank_mask:0xf
	v_add_f32_dpp v204, v204, v204 row_bcast:15 row_mask:0xa bank_mask:0xf
	v_add_f32_dpp v206, v206, v206 row_bcast:15 row_mask:0xa bank_mask:0xf
	v_add_f32_dpp v208, v208, v208 row_bcast:15 row_mask:0xa bank_mask:0xf
	v_add_f32_dpp v147, v147, v147 row_bcast:15 row_mask:0xa bank_mask:0xf
	v_add_f32_dpp v149, v149, v149 row_bcast:31 row_mask:0xc bank_mask:0xf
	v_add_f32_dpp v151, v151, v151 row_bcast:31 row_mask:0xc bank_mask:0xf
	v_add_f32_dpp v153, v153, v153 row_bcast:31 row_mask:0xc bank_mask:0xf
	v_add_f32_dpp v155, v155, v155 row_bcast:31 row_mask:0xc bank_mask:0xf
	v_add_f32_dpp v157, v157, v157 row_bcast:31 row_mask:0xc bank_mask:0xf
	v_add_f32_dpp v159, v159, v159 row_bcast:31 row_mask:0xc bank_mask:0xf
	v_add_f32_dpp v161, v161, v161 row_bcast:31 row_mask:0xc bank_mask:0xf
	v_add_f32_dpp v163, v163, v163 row_bcast:31 row_mask:0xc bank_mask:0xf
	v_add_f32_dpp v165, v165, v165 row_bcast:31 row_mask:0xc bank_mask:0xf
	v_add_f32_dpp v199, v199, v199 row_bcast:31 row_mask:0xc bank_mask:0xf
	v_add_f32_dpp v201, v201, v201 row_bcast:31 row_mask:0xc bank_mask:0xf
	v_add_f32_dpp v203, v203, v203 row_bcast:31 row_mask:0xc bank_mask:0xf
	v_add_f32_dpp v205, v205, v205 row_bcast:31 row_mask:0xc bank_mask:0xf
	v_add_f32_dpp v207, v207, v207 row_bcast:31 row_mask:0xc bank_mask:0xf
	v_add_f32_dpp v209, v209, v209 row_bcast:31 row_mask:0xc bank_mask:0xf
	v_add_f32_dpp v148, v148, v148 row_bcast:31 row_mask:0xc bank_mask:0xf
	v_add_f32_dpp v150, v150, v150 row_bcast:31 row_mask:0xc bank_mask:0xf
	v_add_f32_dpp v152, v152, v152 row_bcast:31 row_mask:0xc bank_mask:0xf
	v_add_f32_dpp v154, v154, v154 row_bcast:31 row_mask:0xc bank_mask:0xf
	v_add_f32_dpp v156, v156, v156 row_bcast:31 row_mask:0xc bank_mask:0xf
	v_add_f32_dpp v158, v158, v158 row_bcast:31 row_mask:0xc bank_mask:0xf
	v_add_f32_dpp v160, v160, v160 row_bcast:31 row_mask:0xc bank_mask:0xf
	v_add_f32_dpp v162, v162, v162 row_bcast:31 row_mask:0xc bank_mask:0xf
	v_add_f32_dpp v164, v164, v164 row_bcast:31 row_mask:0xc bank_mask:0xf
	v_add_f32_dpp v198, v198, v198 row_bcast:31 row_mask:0xc bank_mask:0xf
	v_add_f32_dpp v200, v200, v200 row_bcast:31 row_mask:0xc bank_mask:0xf
	v_add_f32_dpp v202, v202, v202 row_bcast:31 row_mask:0xc bank_mask:0xf
	v_add_f32_dpp v204, v204, v204 row_bcast:31 row_mask:0xc bank_mask:0xf
	v_add_f32_dpp v206, v206, v206 row_bcast:31 row_mask:0xc bank_mask:0xf
	v_add_f32_dpp v208, v208, v208 row_bcast:31 row_mask:0xc bank_mask:0xf
	v_add_f32_dpp v147, v147, v147 row_bcast:31 row_mask:0xc bank_mask:0xf
	v_readlane_b32 s98, v149, 63
	v_readlane_b32 s99, v151, 63
	v_readlane_b32 s100, v153, 63
	v_readlane_b32 s101, v155, 63
	v_writelane_b32 v146, s98, 1
	v_writelane_b32 v146, s99, 2
	v_writelane_b32 v146, s100, 3
	v_writelane_b32 v146, s101, 4
	v_readlane_b32 s98, v157, 63
	v_readlane_b32 s99, v159, 63
	v_readlane_b32 s100, v161, 63
	v_readlane_b32 s101, v163, 63
	v_writelane_b32 v146, s98, 5
	v_writelane_b32 v146, s99, 6
	v_writelane_b32 v146, s100, 7
	v_writelane_b32 v146, s101, 8
	v_readlane_b32 s98, v165, 63
	v_readlane_b32 s99, v199, 63
	v_readlane_b32 s100, v201, 63
	v_readlane_b32 s101, v203, 63
	v_writelane_b32 v146, s98, 9
	v_writelane_b32 v146, s99, 10
	v_writelane_b32 v146, s100, 11
	v_writelane_b32 v146, s101, 12
	v_readlane_b32 s98, v205, 63
	v_readlane_b32 s99, v207, 63
	v_readlane_b32 s100, v209, 63
	v_readlane_b32 s101, v148, 63
	v_writelane_b32 v146, s98, 13
	v_writelane_b32 v146, s99, 14
	v_writelane_b32 v146, s100, 15
	v_writelane_b32 v146, s101, 16
	v_readlane_b32 s98, v150, 63
	v_readlane_b32 s99, v152, 63
	v_readlane_b32 s100, v154, 63
	v_readlane_b32 s101, v156, 63
	v_writelane_b32 v146, s98, 17
	v_writelane_b32 v146, s99, 18
	v_writelane_b32 v146, s100, 19
	v_writelane_b32 v146, s101, 20
	v_readlane_b32 s98, v158, 63
	v_readlane_b32 s99, v160, 63
	v_readlane_b32 s100, v162, 63
	v_readlane_b32 s101, v164, 63
	v_writelane_b32 v146, s98, 21
	v_writelane_b32 v146, s99, 22
	v_writelane_b32 v146, s100, 23
	v_writelane_b32 v146, s101, 24
	v_readlane_b32 s98, v198, 63
	v_readlane_b32 s99, v200, 63
	v_readlane_b32 s100, v202, 63
	v_readlane_b32 s101, v204, 63
	v_writelane_b32 v146, s98, 25
	v_writelane_b32 v146, s99, 26
	v_writelane_b32 v146, s100, 27
	v_writelane_b32 v146, s101, 28
	v_readlane_b32 s98, v206, 63
	v_readlane_b32 s99, v208, 63
	v_readlane_b32 s100, v147, 63
	v_writelane_b32 v146, s98, 29
	v_writelane_b32 v146, s99, 30
	v_writelane_b32 v146, s100, 31
	v_mov_b32_e32 v149, v3
	s_and_saveexec_b64 s[12:13], s[10:11]
	ds_write_b32 v132, v146
	s_or_b64 exec, exec, s[12:13]
	s_waitcnt lgkmcnt(0)
	s_waitcnt lgkmcnt(0)
	s_barrier
; __device__ __forceinline__ void p2_conv_unit_prompt(Frame& F, int unit, int next_pm, const ConvW& cw, size_t src_off = WS_A, size_t dst_off = WS_CACT) {
;     ...
;         if (F.tid < 16) { float s1 = 0.f, s2 = 0.f;
; #pragma unroll
;             for (int w = 0; w < 8; ++w) { s1 += WPT[w * 32 + F.tid]; s2 += WPT[w * 32 + 16 + F.tid]; }
;             const float mean = s1 * (1.0f / DCONV), var = fmaxf(s2 * (1.0f / DCONV) - mean * mean, 0.f);
;             MR[2 * F.tid] = mean; MR[2 * F.tid + 1] = 1.0f / sqrtf(var + EPS); }
	s_and_saveexec_b64 s[42:43], s[6:7]
	s_cbranch_execz .LBB0_465
	ds_read_b32 v1, v15
	ds_read_b32 v146, v48
	ds_read_b32 v147, v49
	ds_read_b32 v148, v50
	ds_read_b32 v149, v51
	ds_read_b32 v150, v52
	ds_read_b32 v151, v53
	ds_read_b32 v152, v54
	s_waitcnt lgkmcnt(7)
	v_add_f32_e32 v1, 0, v1
	s_waitcnt lgkmcnt(6)
	v_add_f32_e32 v146, 0, v146
	s_waitcnt lgkmcnt(5)
	v_add_f32_e32 v1, v1, v147
	s_waitcnt lgkmcnt(4)
	v_add_f32_e32 v146, v146, v148
	s_waitcnt lgkmcnt(3)
	v_add_f32_e32 v1, v1, v149
	s_waitcnt lgkmcnt(2)
	v_add_f32_e32 v146, v146, v150
	s_waitcnt lgkmcnt(1)
	v_add_f32_e32 v1, v1, v151
	s_waitcnt lgkmcnt(0)
	v_add_f32_e32 v146, v146, v152
	ds_read_b32 v147, v55
	ds_read_b32 v148, v56
	ds_read_b32 v149, v57
	ds_read_b32 v150, v122
	ds_read_b32 v151, v123
	ds_read_b32 v152, v124
	ds_read_b32 v153, v125
	ds_read_b32 v154, v126
	s_waitcnt lgkmcnt(7)
	v_add_f32_e32 v1, v1, v147
	s_waitcnt lgkmcnt(6)
	v_add_f32_e32 v146, v146, v148
	s_waitcnt lgkmcnt(5)
	v_add_f32_e32 v1, v1, v149
	s_waitcnt lgkmcnt(4)
	v_add_f32_e32 v146, v146, v150
	s_waitcnt lgkmcnt(3)
	v_add_f32_e32 v1, v1, v151
	s_waitcnt lgkmcnt(2)
	v_add_f32_e32 v146, v146, v152
	s_waitcnt lgkmcnt(1)
	v_add_f32_e32 v1, v1, v153
	s_waitcnt lgkmcnt(0)
	v_add_f32_e32 v147, v146, v154
	v_mul_f32_e32 v146, 0x3a2aaaab, v1
	v_mul_f32_e32 v1, v146, v146
	v_fma_f32 v1, v147, s55, -v1
	v_max_f32_e32 v1, 0, v1
	v_add_f32_e32 v1, 0x358637bd, v1
	v_mul_f32_e32 v147, 0x4f800000, v1
	v_cmp_gt_f32_e32 vcc, s56, v1
	s_nop 1
	v_cndmask_b32_e32 v1, v1, v147, vcc
	v_sqrt_f32_e32 v147, v1
	s_nop 0
	v_add_u32_e32 v148, -1, v147
	v_fma_f32 v149, -v148, v147, v1
	v_cmp_ge_f32_e64 s[12:13], 0, v149
	v_add_u32_e32 v149, 1, v147
	s_nop 0
	v_cndmask_b32_e64 v148, v147, v148, s[12:13]
	v_fma_f32 v147, -v149, v147, v1
	v_cmp_lt_f32_e64 s[12:13], 0, v147
	s_nop 1
	v_cndmask_b32_e64 v147, v148, v149, s[12:13]
	v_mul_f32_e32 v148, 0x37800000, v147
	v_cndmask_b32_e32 v147, v147, v148, vcc
	v_cmp_class_f32_e32 vcc, v1, v128
	s_nop 1
	v_cndmask_b32_e32 v1, v147, v1, vcc
	v_div_scale_f32 v147, s[12:13], v1, v1, 1.0
	v_rcp_f32_e32 v148, v147
	s_nop 0
	v_fma_f32 v149, -v147, v148, 1.0
	v_fmac_f32_e32 v148, v149, v148
	v_div_scale_f32 v149, vcc, 1.0, v1, 1.0
	v_mul_f32_e32 v150, v149, v148
	v_fma_f32 v151, -v147, v150, v149
	v_fmac_f32_e32 v150, v151, v148
	v_fma_f32 v147, -v147, v150, v149
	v_div_fmas_f32 v147, v147, v148, v150
	v_div_fixup_f32 v147, v147, v1, 1.0
	ds_write_b64 v127, v[146:147]
	s_branch .LBB0_465
